# S5 GLU K-loop fully unrolled: 5 weight fragment sets in flight (prefetch distance 4 k-steps, saddr loads), LDS reads pipelined one step ahead
# speedup vs baseline: 1.0075x; 1.0075x over previous
.LBB0_464:
	v_ashrrev_i32_e32 v151, 31, v150
	v_lshlrev_b64 v[6:7], 9, v[150:151]
	v_lshl_add_u64 v[38:39], v[148:149], 0, v[6:7]
	global_load_dwordx4 v[40:43], v[38:39], off
	global_load_dwordx4 v[44:47], v[38:39], off offset:1024
	global_load_dwordx4 v[48:51], v[38:39], off offset:2048
	global_load_dwordx4 v[52:55], v[38:39], off offset:3072
	v_add_co_u32_e32 v6, vcc, s12, v38
	s_movk_i32 s4, 0x3000
	s_nop 0
	v_addc_co_u32_e32 v7, vcc, 0, v39, vcc
	v_add_co_u32_e32 v8, vcc, s68, v38
	v_add_u32_e32 v151, s22, v243
	s_nop 0
	v_addc_co_u32_e32 v9, vcc, 0, v39, vcc
	v_add_co_u32_e32 v14, vcc, s4, v38
	global_load_dwordx4 v[56:59], v[8:9], off offset:-4096
	global_load_dwordx4 v[60:63], v[6:7], off offset:1024
	global_load_dwordx4 v[64:67], v[6:7], off offset:2048
	global_load_dwordx4 v[68:71], v[6:7], off offset:3072
	global_load_dwordx4 v[26:29], v[8:9], off
	global_load_dwordx4 v[18:21], v[8:9], off offset:1024
	global_load_dwordx4 v[10:13], v[8:9], off offset:2048
	s_nop 0
	global_load_dwordx4 v[6:9], v[8:9], off offset:3072
	v_addc_co_u32_e32 v15, vcc, 0, v39, vcc
	v_add_co_u32_e32 v88, vcc, s69, v38
	s_movk_i32 s4, 0x5000
	s_nop 0
	v_addc_co_u32_e32 v89, vcc, 0, v39, vcc
	global_load_dwordx4 v[34:37], v[88:89], off offset:-4096
	global_load_dwordx4 v[30:33], v[14:15], off offset:1024
	global_load_dwordx4 v[22:25], v[14:15], off offset:2048
	s_nop 0
	global_load_dwordx4 v[14:17], v[14:15], off offset:3072
	ds_read_b128 v[72:75], v151 offset:14560
	ds_read_b128 v[76:79], v151 offset:31200
	ds_read_b128 v[80:83], v151 offset:47840
	ds_read_b128 v[84:87], v151 offset:64480
	v_ashrrev_i32_e32 v157, 31, v156
	v_add_u32_e32 v150, 64, v150
	v_add_u32_e32 v243, 32, v243
	s_waitcnt vmcnt(15) lgkmcnt(3)
	v_mfma_f32_16x16x32_bf16 v[72:75], v[40:43], v[72:75], 0
	s_waitcnt lgkmcnt(2)
	v_mfma_f32_16x16x32_bf16 v[76:79], v[40:43], v[76:79], 0
	s_waitcnt lgkmcnt(1)
	v_mfma_f32_16x16x32_bf16 v[80:83], v[40:43], v[80:83], 0
	s_waitcnt lgkmcnt(0)
	v_mfma_f32_16x16x32_bf16 v[40:43], v[40:43], v[84:87], 0
	ds_read_b128 v[84:87], v151 offset:12480
	s_waitcnt vmcnt(14) lgkmcnt(0)
	v_mfma_f32_16x16x32_bf16 v[72:75], v[44:47], v[84:87], v[72:75]
	ds_read_b128 v[84:87], v151 offset:29120
	s_waitcnt lgkmcnt(0)
	v_mfma_f32_16x16x32_bf16 v[76:79], v[44:47], v[84:87], v[76:79]
	ds_read_b128 v[84:87], v151 offset:45760
	s_waitcnt lgkmcnt(0)
	v_mfma_f32_16x16x32_bf16 v[80:83], v[44:47], v[84:87], v[80:83]
	ds_read_b128 v[84:87], v151 offset:62400
	s_waitcnt lgkmcnt(0)
	v_mfma_f32_16x16x32_bf16 v[40:43], v[44:47], v[84:87], v[40:43]
	ds_read_b128 v[44:47], v151 offset:10400
	s_waitcnt vmcnt(13) lgkmcnt(0)
	v_mfma_f32_16x16x32_bf16 v[44:47], v[48:51], v[44:47], v[72:75]
	s_nop 2
	ds_read_b128 v[72:75], v151 offset:27040
	s_waitcnt lgkmcnt(0)
	v_mfma_f32_16x16x32_bf16 v[72:75], v[48:51], v[72:75], v[76:79]
	s_nop 2
	ds_read_b128 v[76:79], v151 offset:43680
	s_waitcnt lgkmcnt(0)
	v_mfma_f32_16x16x32_bf16 v[76:79], v[48:51], v[76:79], v[80:83]
	s_nop 2
	ds_read_b128 v[80:83], v151 offset:60320
	s_waitcnt lgkmcnt(0)
	v_mfma_f32_16x16x32_bf16 v[40:43], v[48:51], v[80:83], v[40:43]
	ds_read_b128 v[48:51], v151 offset:8320
	s_waitcnt vmcnt(12) lgkmcnt(0)
	v_mfma_f32_16x16x32_bf16 v[44:47], v[52:55], v[48:51], v[44:47]
	ds_read_b128 v[48:51], v151 offset:24960
	s_waitcnt lgkmcnt(0)
	v_mfma_f32_16x16x32_bf16 v[48:51], v[52:55], v[48:51], v[72:75]
	s_nop 2
	ds_read_b128 v[72:75], v151 offset:41600
	s_waitcnt lgkmcnt(0)
	v_mfma_f32_16x16x32_bf16 v[72:75], v[52:55], v[72:75], v[76:79]
	s_nop 2
	ds_read_b128 v[76:79], v151 offset:58240
	s_waitcnt lgkmcnt(0)
	v_mfma_f32_16x16x32_bf16 v[40:43], v[52:55], v[76:79], v[40:43]
	ds_read_b128 v[52:55], v151 offset:6240
	s_waitcnt vmcnt(11) lgkmcnt(0)
	v_mfma_f32_16x16x32_bf16 v[44:47], v[56:59], v[52:55], v[44:47]
	ds_read_b128 v[52:55], v151 offset:22880
	s_waitcnt lgkmcnt(0)
	v_mfma_f32_16x16x32_bf16 v[48:51], v[56:59], v[52:55], v[48:51]
	ds_read_b128 v[52:55], v151 offset:39520
	s_waitcnt lgkmcnt(0)
	v_mfma_f32_16x16x32_bf16 v[52:55], v[56:59], v[52:55], v[72:75]
	s_nop 2
	ds_read_b128 v[72:75], v151 offset:56160
	s_waitcnt lgkmcnt(0)
	v_mfma_f32_16x16x32_bf16 v[40:43], v[56:59], v[72:75], v[40:43]
	ds_read_b128 v[56:59], v151 offset:4160
	s_waitcnt vmcnt(10) lgkmcnt(0)
	v_mfma_f32_16x16x32_bf16 v[44:47], v[60:63], v[56:59], v[44:47]
	ds_read_b128 v[56:59], v151 offset:20800
	s_waitcnt lgkmcnt(0)
	v_mfma_f32_16x16x32_bf16 v[48:51], v[60:63], v[56:59], v[48:51]
	ds_read_b128 v[56:59], v151 offset:37440
	s_waitcnt lgkmcnt(0)
	v_mfma_f32_16x16x32_bf16 v[52:55], v[60:63], v[56:59], v[52:55]
	ds_read_b128 v[56:59], v151 offset:54080
	s_waitcnt lgkmcnt(0)
	v_mfma_f32_16x16x32_bf16 v[40:43], v[60:63], v[56:59], v[40:43]
	ds_read_b128 v[56:59], v151 offset:2080
	s_waitcnt vmcnt(9) lgkmcnt(0)
	v_mfma_f32_16x16x32_bf16 v[44:47], v[64:67], v[56:59], v[44:47]
	ds_read_b128 v[56:59], v151 offset:18720
	s_waitcnt lgkmcnt(0)
	v_mfma_f32_16x16x32_bf16 v[48:51], v[64:67], v[56:59], v[48:51]
	ds_read_b128 v[56:59], v151 offset:35360
	s_waitcnt lgkmcnt(0)
	v_mfma_f32_16x16x32_bf16 v[58:61], v[64:67], v[56:59], v[52:55]
	s_nop 2
	ds_read_b128 v[52:55], v151 offset:52000
	s_waitcnt lgkmcnt(0)
	v_mfma_f32_16x16x32_bf16 v[40:43], v[64:67], v[52:55], v[40:43]
	ds_read_b128 v[52:55], v151
	s_waitcnt vmcnt(8) lgkmcnt(0)
	v_mfma_f32_16x16x32_bf16 v[54:57], v[68:71], v[52:55], v[44:47]
	v_add_co_u32_e32 v52, vcc, s4, v38
	s_nop 1
	ds_read_b128 v[44:47], v151 offset:16640
	s_waitcnt lgkmcnt(0)
	v_mfma_f32_16x16x32_bf16 v[44:47], v[68:71], v[44:47], v[48:51]
	s_nop 2
	ds_read_b128 v[48:51], v151 offset:33280
	v_addc_co_u32_e32 v53, vcc, 0, v39, vcc
	s_waitcnt lgkmcnt(0)
	v_mfma_f32_16x16x32_bf16 v[48:51], v[68:71], v[48:51], v[58:61]
	v_add_co_u32_e32 v102, vcc, s70, v38
	s_nop 1
	ds_read_b128 v[58:61], v151 offset:49920
	v_addc_co_u32_e32 v103, vcc, 0, v39, vcc
	s_waitcnt lgkmcnt(0)
	v_mfma_f32_16x16x32_bf16 v[40:43], v[68:71], v[58:61], v[40:43]
	global_load_dwordx4 v[70:73], v[88:89], off
	global_load_dwordx4 v[66:69], v[88:89], off offset:1024
	global_load_dwordx4 v[62:65], v[88:89], off offset:2048
	global_load_dwordx4 v[58:61], v[88:89], off offset:3072
	s_nop 0
	global_load_dwordx4 v[86:89], v[102:103], off offset:-4096
	global_load_dwordx4 v[82:85], v[52:53], off offset:1024
	global_load_dwordx4 v[78:81], v[52:53], off offset:2048
	global_load_dwordx4 v[74:77], v[52:53], off offset:3072
	ds_read_b128 v[90:93], v151 offset:14560
	s_waitcnt vmcnt(15) lgkmcnt(0)
	v_mfma_f32_16x16x32_bf16 v[44:47], v[26:29], v[90:93], v[44:47]
	ds_read_b128 v[90:93], v151 offset:31200
	s_movk_i32 s4, 0x7000
	s_waitcnt lgkmcnt(0)
	v_mfma_f32_16x16x32_bf16 v[48:51], v[26:29], v[90:93], v[48:51]
	ds_read_b128 v[90:93], v151 offset:47840
	s_waitcnt lgkmcnt(0)
	v_mfma_f32_16x16x32_bf16 v[26:29], v[26:29], v[90:93], v[40:43]
	s_nop 2
	ds_read_b128 v[40:43], v151 offset:12480
	s_waitcnt vmcnt(14) lgkmcnt(0)
	v_mfma_f32_16x16x32_bf16 v[40:43], v[18:21], v[40:43], v[44:47]
	s_nop 2
	ds_read_b128 v[44:47], v151 offset:29120
	s_waitcnt lgkmcnt(0)
	v_mfma_f32_16x16x32_bf16 v[44:47], v[18:21], v[44:47], v[48:51]
	s_nop 2
	ds_read_b128 v[48:51], v151 offset:45760
	s_waitcnt lgkmcnt(0)
	v_mfma_f32_16x16x32_bf16 v[18:21], v[18:21], v[48:51], v[26:29]
	s_nop 2
	ds_read_b128 v[26:29], v151 offset:10400
	s_waitcnt vmcnt(13) lgkmcnt(0)
	v_mfma_f32_16x16x32_bf16 v[26:29], v[10:13], v[26:29], v[40:43]
	s_nop 2
	ds_read_b128 v[40:43], v151 offset:27040
	s_waitcnt lgkmcnt(0)
	v_mfma_f32_16x16x32_bf16 v[40:43], v[10:13], v[40:43], v[44:47]
	s_nop 2
	ds_read_b128 v[44:47], v151 offset:43680
	s_waitcnt lgkmcnt(0)
	v_mfma_f32_16x16x32_bf16 v[10:13], v[10:13], v[44:47], v[18:21]
	s_nop 2
	ds_read_b128 v[18:21], v151 offset:8320
	s_waitcnt vmcnt(12) lgkmcnt(0)
	v_mfma_f32_16x16x32_bf16 v[18:21], v[6:9], v[18:21], v[26:29]
	s_nop 2
	ds_read_b128 v[26:29], v151 offset:24960
	s_waitcnt lgkmcnt(0)
	v_mfma_f32_16x16x32_bf16 v[26:29], v[6:9], v[26:29], v[40:43]
	s_nop 2
	ds_read_b128 v[40:43], v151 offset:41600
	s_waitcnt lgkmcnt(0)
	v_mfma_f32_16x16x32_bf16 v[6:9], v[6:9], v[40:43], v[10:13]
	s_nop 2
	ds_read_b128 v[10:13], v151 offset:6240
	s_waitcnt vmcnt(11) lgkmcnt(0)
	v_mfma_f32_16x16x32_bf16 v[10:13], v[34:37], v[10:13], v[18:21]
	s_nop 2
	ds_read_b128 v[18:21], v151 offset:22880
	s_waitcnt lgkmcnt(0)
	v_mfma_f32_16x16x32_bf16 v[18:21], v[34:37], v[18:21], v[26:29]
	s_nop 2
	ds_read_b128 v[26:29], v151 offset:39520
	s_waitcnt lgkmcnt(0)
	v_mfma_f32_16x16x32_bf16 v[6:9], v[34:37], v[26:29], v[6:9]
	ds_read_b128 v[26:29], v151 offset:4160
	s_waitcnt vmcnt(10) lgkmcnt(0)
	v_mfma_f32_16x16x32_bf16 v[10:13], v[30:33], v[26:29], v[10:13]
	ds_read_b128 v[26:29], v151 offset:20800
	s_waitcnt lgkmcnt(0)
	v_mfma_f32_16x16x32_bf16 v[18:21], v[30:33], v[26:29], v[18:21]
	ds_read_b128 v[26:29], v151 offset:37440
	s_waitcnt lgkmcnt(0)
	v_mfma_f32_16x16x32_bf16 v[6:9], v[30:33], v[26:29], v[6:9]
	ds_read_b128 v[26:29], v151 offset:2080
	s_waitcnt vmcnt(9) lgkmcnt(0)
	v_mfma_f32_16x16x32_bf16 v[10:13], v[22:25], v[26:29], v[10:13]
	ds_read_b128 v[26:29], v151 offset:18720
	s_waitcnt lgkmcnt(0)
	v_mfma_f32_16x16x32_bf16 v[18:21], v[22:25], v[26:29], v[18:21]
	ds_read_b128 v[26:29], v151 offset:35360
	s_waitcnt lgkmcnt(0)
	v_mfma_f32_16x16x32_bf16 v[6:9], v[22:25], v[26:29], v[6:9]
	ds_read_b128 v[22:25], v151
	v_lshl_add_u64 v[26:27], v[156:157], 3, s[0:1]
	v_add_u32_e32 v156, 64, v156
	s_waitcnt vmcnt(8) lgkmcnt(0)
	v_mfma_f32_16x16x32_bf16 v[50:53], v[14:17], v[22:25], v[10:13]
	s_nop 2
	ds_read_b128 v[10:13], v151 offset:16640
	s_waitcnt lgkmcnt(0)
	v_mfma_f32_16x16x32_bf16 v[106:109], v[14:17], v[10:13], v[18:21]
	ds_read_b128 v[10:13], v151 offset:33280
	global_load_dwordx4 v[90:93], v[102:103], off
	global_load_dwordx4 v[94:97], v[102:103], off offset:1024
	global_load_dwordx4 v[98:101], v[102:103], off offset:2048
	s_nop 0
	global_load_dwordx4 v[102:105], v[102:103], off offset:3072
	s_waitcnt lgkmcnt(0)
	v_mfma_f32_16x16x32_bf16 v[110:113], v[14:17], v[10:13], v[6:9]
	s_nop 2
	v_add_co_u32_e32 v6, vcc, s4, v38
	v_add_u32_e32 v8, s23, v239
	s_nop 0
	v_addc_co_u32_e32 v7, vcc, 0, v39, vcc
	global_load_dwordx4 v[118:121], v[6:7], off
	global_load_dwordx4 v[122:125], v[6:7], off offset:1024
	global_load_dwordx4 v[126:129], v[6:7], off offset:2048
	global_load_dwordx4 v[130:133], v[6:7], off offset:3072
	global_load_dwordx4 v[46:49], v[152:153], off offset:-128
	v_add_u32_e32 v6, s23, v240
	v_ashrrev_i32_e32 v7, 31, v6
	v_lshl_add_u64 v[10:11], v[6:7], 3, s[96:97]
	v_ashrrev_i32_e32 v9, 31, v8
	global_load_dwordx2 v[218:219], v[10:11], off offset:8
	v_lshl_add_u64 v[10:11], v[8:9], 3, s[96:97]
	global_load_dwordx2 v[208:209], v[10:11], off offset:128
	v_add_u32_e32 v10, 17, v8
	v_add_u32_e32 v12, 17, v6
	v_ashrrev_i32_e32 v13, 31, v12
	v_ashrrev_i32_e32 v11, 31, v10
	v_lshl_add_u64 v[12:13], v[12:13], 3, s[96:97]
	v_lshl_add_u64 v[10:11], v[10:11], 3, s[96:97]
	global_load_dwordx4 v[114:117], v[26:27], off offset:16
	global_load_dwordx4 v[134:137], v[26:27], off
	global_load_dwordx2 v[214:215], v[12:13], off offset:8
	global_load_dwordx2 v[206:207], v[10:11], off offset:128
	v_add_u32_e32 v10, 34, v8
	v_add_u32_e32 v12, 34, v6
	v_ashrrev_i32_e32 v13, 31, v12
	v_ashrrev_i32_e32 v11, 31, v10
	v_lshl_add_u64 v[12:13], v[12:13], 3, s[96:97]
	v_lshl_add_u64 v[10:11], v[10:11], 3, s[96:97]
	global_load_dwordx2 v[220:221], v[12:13], off offset:8
	global_load_dwordx2 v[212:213], v[10:11], off offset:128
	v_add_u32_e32 v10, 51, v8
	v_add_u32_e32 v12, 51, v6
	v_ashrrev_i32_e32 v13, 31, v12
	v_ashrrev_i32_e32 v11, 31, v10
	v_lshl_add_u64 v[12:13], v[12:13], 3, s[96:97]
	v_lshl_add_u64 v[10:11], v[10:11], 3, s[96:97]
	global_load_dwordx2 v[216:217], v[12:13], off offset:8
	global_load_dwordx2 v[210:211], v[10:11], off offset:128
	global_load_dwordx4 v[34:37], v[152:153], off offset:-64
	v_add_u32_e32 v10, 0x110, v8
	v_add_u32_e32 v12, 0x110, v6
	v_ashrrev_i32_e32 v13, 31, v12
	v_ashrrev_i32_e32 v11, 31, v10
	v_lshl_add_u64 v[12:13], v[12:13], 3, s[96:97]
	v_lshl_add_u64 v[10:11], v[10:11], 3, s[96:97]
	global_load_dwordx2 v[202:203], v[12:13], off offset:8
	global_load_dwordx2 v[192:193], v[10:11], off offset:128
	global_load_dwordx4 v[38:41], v[26:27], off offset:144
	global_load_dwordx4 v[42:45], v[26:27], off offset:128
	v_add_u32_e32 v10, 0x121, v8
	v_add_u32_e32 v12, 0x121, v6
	v_ashrrev_i32_e32 v13, 31, v12
	v_ashrrev_i32_e32 v11, 31, v10
	v_lshl_add_u64 v[12:13], v[12:13], 3, s[96:97]
	v_lshl_add_u64 v[10:11], v[10:11], 3, s[96:97]
	global_load_dwordx2 v[198:199], v[12:13], off offset:8
	global_load_dwordx2 v[190:191], v[10:11], off offset:128
	v_add_u32_e32 v10, 0x132, v8
	v_add_u32_e32 v12, 0x132, v6
	v_ashrrev_i32_e32 v13, 31, v12
	v_ashrrev_i32_e32 v11, 31, v10
	v_lshl_add_u64 v[12:13], v[12:13], 3, s[96:97]
	v_lshl_add_u64 v[10:11], v[10:11], 3, s[96:97]
	global_load_dwordx2 v[204:205], v[12:13], off offset:8
	global_load_dwordx2 v[196:197], v[10:11], off offset:128
	v_add_u32_e32 v10, 0x143, v8
	v_add_u32_e32 v12, 0x143, v6
	v_ashrrev_i32_e32 v13, 31, v12
	v_ashrrev_i32_e32 v11, 31, v10
	v_lshl_add_u64 v[12:13], v[12:13], 3, s[96:97]
	v_lshl_add_u64 v[10:11], v[10:11], 3, s[96:97]
	global_load_dwordx2 v[200:201], v[12:13], off offset:8
	global_load_dwordx2 v[194:195], v[10:11], off offset:128
	global_load_dwordx4 v[14:17], v[152:153], off
	v_add_u32_e32 v10, 0x220, v8
	v_add_u32_e32 v12, 0x220, v6
	v_ashrrev_i32_e32 v13, 31, v12
	v_ashrrev_i32_e32 v11, 31, v10
	v_lshl_add_u64 v[12:13], v[12:13], 3, s[96:97]
	v_lshl_add_u64 v[10:11], v[10:11], 3, s[96:97]
	global_load_dwordx2 v[184:185], v[12:13], off offset:8
	global_load_dwordx2 v[178:179], v[10:11], off offset:128
	global_load_dwordx4 v[22:25], v[26:27], off offset:272
	global_load_dwordx4 v[30:33], v[26:27], off offset:256
	v_add_u32_e32 v10, 0x231, v8
	v_add_u32_e32 v12, 0x231, v6
	v_ashrrev_i32_e32 v13, 31, v12
	v_ashrrev_i32_e32 v11, 31, v10
	v_lshl_add_u64 v[12:13], v[12:13], 3, s[96:97]
	v_lshl_add_u64 v[10:11], v[10:11], 3, s[96:97]
	global_load_dwordx2 v[182:183], v[12:13], off offset:8
	global_load_dwordx2 v[172:173], v[10:11], off offset:128
	v_add_u32_e32 v10, 0x242, v8
	v_add_u32_e32 v12, 0x242, v6
	v_ashrrev_i32_e32 v13, 31, v12
	v_ashrrev_i32_e32 v11, 31, v10
	v_lshl_add_u64 v[12:13], v[12:13], 3, s[96:97]
	v_lshl_add_u64 v[10:11], v[10:11], 3, s[96:97]
	global_load_dwordx2 v[186:187], v[12:13], off offset:8
	global_load_dwordx2 v[180:181], v[10:11], off offset:128
	v_add_u32_e32 v10, 0x253, v8
	v_add_u32_e32 v12, 0x253, v6
	v_add_u32_e32 v18, 0x330, v8
	v_add_u32_e32 v20, 0x330, v6
	v_add_u32_e32 v140, 0x341, v8
	v_add_u32_e32 v142, 0x341, v6
	v_ashrrev_i32_e32 v13, 31, v12
	v_ashrrev_i32_e32 v11, 31, v10
	v_ashrrev_i32_e32 v21, 31, v20
	v_ashrrev_i32_e32 v19, 31, v18
	v_ashrrev_i32_e32 v143, 31, v142
	v_ashrrev_i32_e32 v141, 31, v140
	v_lshl_add_u64 v[12:13], v[12:13], 3, s[96:97]
	v_lshl_add_u64 v[10:11], v[10:11], 3, s[96:97]
	v_lshl_add_u64 v[20:21], v[20:21], 3, s[96:97]
	v_lshl_add_u64 v[18:19], v[18:19], 3, s[96:97]
	v_lshl_add_u64 v[142:143], v[142:143], 3, s[96:97]
	v_lshl_add_u64 v[140:141], v[140:141], 3, s[96:97]
	global_load_dwordx2 v[176:177], v[12:13], off offset:8
	global_load_dwordx2 v[170:171], v[10:11], off offset:128
	s_nop 0
	global_load_dwordx4 v[10:13], v[152:153], off offset:64
	global_load_dwordx2 v[162:163], v[20:21], off offset:8
	global_load_dwordx2 v[160:161], v[18:19], off offset:128
	s_nop 0
	global_load_dwordx4 v[18:21], v[26:27], off offset:400
	s_nop 0
	global_load_dwordx4 v[26:29], v[26:27], off offset:384
	s_addk_i32 s23, 0x440
	global_load_dwordx2 v[164:165], v[142:143], off offset:8
	global_load_dwordx2 v[158:159], v[140:141], off offset:128
	v_add_u32_e32 v142, 0x352, v6
	v_add_u32_e32 v6, 0x363, v6
	v_ashrrev_i32_e32 v7, 31, v6
	v_lshl_add_u64 v[6:7], v[6:7], 3, s[96:97]
	global_load_dwordx2 v[174:175], v[6:7], off offset:8
	v_add_u32_e32 v140, 0x352, v8
	v_add_u32_e32 v8, 0x363, v8
	v_ashrrev_i32_e32 v143, 31, v142
	v_ashrrev_i32_e32 v141, 31, v140
	v_ashrrev_i32_e32 v9, 31, v8
	v_lshl_add_u64 v[142:143], v[142:143], 3, s[96:97]
	v_lshl_add_u64 v[140:141], v[140:141], 3, s[96:97]
	v_lshl_add_u64 v[6:7], v[8:9], 3, s[96:97]
	global_load_dwordx2 v[168:169], v[142:143], off offset:8
	global_load_dwordx2 v[166:167], v[140:141], off offset:128
	global_load_dwordx2 v[188:189], v[6:7], off offset:128
	s_nop 0
	global_load_dwordx4 v[6:9], v[154:155], off
	ds_read_b128 v[244:247], v151 offset:14560
	ds_read_b128 v[140:143], v151 offset:31200
	s_waitcnt vmcnt(60) lgkmcnt(1)
	v_mfma_f32_16x16x32_bf16 v[106:109], v[70:73], v[244:247], v[106:109]
	v_lshl_add_u64 v[152:153], v[152:153], 0, s[14:15]
	v_lshl_add_u64 v[154:155], v[154:155], 0, 64
	s_cmpk_eq_i32 s23, 0x1100
	s_waitcnt lgkmcnt(0)
	v_mfma_f32_16x16x32_bf16 v[70:73], v[70:73], v[140:143], v[110:113]
	ds_read_b128 v[140:143], v151 offset:29120
	s_nop 1
	ds_read_b128 v[110:113], v151 offset:12480
	s_waitcnt vmcnt(59) lgkmcnt(0)
	v_mfma_f32_16x16x32_bf16 v[106:109], v[66:69], v[110:113], v[106:109]
	v_mfma_f32_16x16x32_bf16 v[66:69], v[66:69], v[140:143], v[70:73]
	ds_read_b128 v[140:143], v151 offset:27040
	s_nop 1
	ds_read_b128 v[70:73], v151 offset:10400
	s_waitcnt vmcnt(58) lgkmcnt(0)
	v_mfma_f32_16x16x32_bf16 v[106:109], v[62:65], v[70:73], v[106:109]
	v_mfma_f32_16x16x32_bf16 v[62:65], v[62:65], v[140:143], v[66:69]
	ds_read_b128 v[140:143], v151 offset:24960
	s_nop 1
	ds_read_b128 v[66:69], v151 offset:8320
	s_waitcnt vmcnt(57) lgkmcnt(0)
	v_mfma_f32_16x16x32_bf16 v[106:109], v[58:61], v[66:69], v[106:109]
	v_mfma_f32_16x16x32_bf16 v[58:61], v[58:61], v[140:143], v[62:65]
	ds_read_b128 v[140:143], v151 offset:6240
	s_waitcnt vmcnt(56) lgkmcnt(0)
	v_mfma_f32_16x16x32_bf16 v[62:65], v[86:89], v[140:143], v[106:109]
	s_nop 3
	ds_read_b128 v[106:109], v151 offset:22880
	s_waitcnt lgkmcnt(0)
	v_mfma_f32_16x16x32_bf16 v[58:61], v[86:89], v[106:109], v[58:61]
	ds_read_b128 v[86:89], v151 offset:4160
	ds_read_b128 v[106:109], v151 offset:20800
	s_waitcnt vmcnt(55) lgkmcnt(1)
	v_mfma_f32_16x16x32_bf16 v[62:65], v[82:85], v[86:89], v[62:65]
	s_waitcnt lgkmcnt(0)
	v_mfma_f32_16x16x32_bf16 v[58:61], v[82:85], v[106:109], v[58:61]
	ds_read_b128 v[82:85], v151 offset:2080
	ds_read_b128 v[106:109], v151 offset:18720
	s_waitcnt vmcnt(54) lgkmcnt(1)
	v_mfma_f32_16x16x32_bf16 v[62:65], v[78:81], v[82:85], v[62:65]
	s_waitcnt lgkmcnt(0)
	v_mfma_f32_16x16x32_bf16 v[58:61], v[78:81], v[106:109], v[58:61]
	ds_read_b128 v[78:81], v151
	ds_read_b128 v[106:109], v151 offset:16640
	s_waitcnt vmcnt(53) lgkmcnt(0)
	v_mfma_f32_16x16x32_bf16 v[58:61], v[74:77], v[106:109], v[58:61]
	s_waitcnt vmcnt(52)
	v_mfma_f32_16x16x32_bf16 v[58:61], v[90:93], v[244:247], v[58:61]
	s_waitcnt vmcnt(51)
	v_mfma_f32_16x16x32_bf16 v[58:61], v[94:97], v[110:113], v[58:61]
	s_waitcnt vmcnt(50)
	v_mfma_f32_16x16x32_bf16 v[58:61], v[98:101], v[70:73], v[58:61]
	s_waitcnt vmcnt(40)
	v_mov_b32_e32 v72, v134
	v_mov_b32_e32 v73, v136
	v_mov_b32_e32 v70, v114
	v_mfma_f32_16x16x32_bf16 v[58:61], v[102:105], v[66:69], v[58:61]
	v_mov_b32_e32 v71, v116
	v_mov_b32_e32 v136, v135
	v_mov_b32_e32 v116, v115
	v_mfma_f32_16x16x32_bf16 v[58:61], v[118:121], v[140:143], v[58:61]
	v_mfma_f32_16x16x32_bf16 v[58:61], v[122:125], v[86:89], v[58:61]
	v_mfma_f32_16x16x32_bf16 v[58:61], v[126:129], v[82:85], v[58:61]
	v_mfma_f32_16x16x32_bf16 v[62:65], v[74:77], v[78:81], v[62:65]
	s_waitcnt vmcnt(39)
	v_mov_b32_e32 v75, v214
	v_mov_b32_e32 v214, v219
	s_waitcnt vmcnt(35)
	v_mov_b32_e32 v77, v216
	v_mov_b32_e32 v216, v221
	v_mfma_f32_16x16x32_bf16 v[66:69], v[130:133], v[78:81], v[58:61]
	v_mov_b32_e32 v74, v218
	v_mov_b32_e32 v76, v220
	v_pk_mul_f32 v[80:81], v[216:217], v[70:71]
	v_pk_mul_f32 v[60:61], v[214:215], v[72:73]
	v_pk_mul_f32 v[58:59], v[214:215], v[136:137]
	v_pk_fma_f32 v[60:61], v[74:75], v[136:137], v[60:61]
	v_pk_mul_f32 v[78:79], v[216:217], v[116:117]
	v_pk_fma_f32 v[80:81], v[76:77], v[116:117], v[80:81]
	v_pk_fma_f32 v[58:59], v[74:75], v[72:73], v[58:59] neg_lo:[0,0,1] neg_hi:[0,0,1]
	v_pk_fma_f32 v[78:79], v[76:77], v[70:71], v[78:79] neg_lo:[0,0,1] neg_hi:[0,0,1]
	v_cvt_pk_bf16_f32 v59, v59, v61
	v_cvt_pk_bf16_f32 v61, v79, v81
	v_cvt_pk_bf16_f32 v58, v58, v60
	v_cvt_pk_bf16_f32 v60, v78, v80
	v_mov_b32_e32 v79, v206
	v_mov_b32_e32 v206, v209
	v_mfma_f32_16x16x32_bf16 v[54:57], v[46:49], v[58:61], v[54:57]
	v_mov_b32_e32 v78, v208
	v_pk_mul_f32 v[58:59], v[214:215], v[206:207]
	v_mov_b32_e32 v82, v212
	s_waitcnt vmcnt(34)
	v_mov_b32_e32 v83, v210
	v_mov_b32_e32 v210, v213
	v_pk_fma_f32 v[80:81], v[74:75], v[78:79], v[58:59] neg_lo:[0,0,1] neg_hi:[0,0,1]
	v_pk_mul_f32 v[58:59], v[214:215], v[78:79]
	v_pk_mul_f32 v[84:85], v[216:217], v[210:211]
	v_pk_mul_f32 v[86:87], v[216:217], v[82:83]
	v_pk_fma_f32 v[74:75], v[74:75], v[206:207], v[58:59]
	v_pk_fma_f32 v[84:85], v[76:77], v[82:83], v[84:85] neg_lo:[0,0,1] neg_hi:[0,0,1]
	v_pk_fma_f32 v[76:77], v[76:77], v[210:211], v[86:87]
	v_pk_mul_f32 v[60:61], v[72:73], v[74:75]
	v_pk_mul_f32 v[88:89], v[70:71], v[76:77]
	v_pk_mul_f32 v[58:59], v[136:137], v[74:75]
	v_pk_fma_f32 v[60:61], v[136:137], v[80:81], v[60:61]
	v_pk_mul_f32 v[86:87], v[116:117], v[76:77]
	v_pk_fma_f32 v[88:89], v[116:117], v[84:85], v[88:89]
	v_pk_fma_f32 v[58:59], v[72:73], v[80:81], v[58:59] neg_lo:[0,0,1] neg_hi:[0,0,1]
	v_pk_fma_f32 v[86:87], v[70:71], v[84:85], v[86:87] neg_lo:[0,0,1] neg_hi:[0,0,1]
	v_cvt_pk_bf16_f32 v59, v59, v61
	v_cvt_pk_bf16_f32 v61, v87, v89
	v_cvt_pk_bf16_f32 v58, v58, v60
	v_cvt_pk_bf16_f32 v60, v86, v88
	s_nop 1
	v_mfma_f32_16x16x32_bf16 v[58:61], v[46:49], v[58:61], v[50:53]
	s_nop 2
	v_mul_f32_e64 v52, v78, v74
	v_mul_f32_e64 v53, v79, v75
	v_pk_mul_f32 v[50:51], v[206:207], v[74:75]
	v_pk_fma_f32 v[52:53], v[206:207], v[80:81], v[52:53]
	v_pk_fma_f32 v[50:51], v[78:79], v[80:81], v[50:51] neg_lo:[0,0,1] neg_hi:[0,0,1]
	v_pk_mul_f32 v[74:75], v[136:137], v[52:53]
	v_pk_mul_f32 v[80:81], v[72:73], v[52:53]
	v_pk_mul_f32 v[86:87], v[206:207], v[52:53]
	v_pk_mul_f32 v[52:53], v[78:79], v[52:53]
	v_pk_fma_f32 v[74:75], v[72:73], v[50:51], v[74:75] neg_lo:[0,0,1] neg_hi:[0,0,1]
	v_pk_fma_f32 v[80:81], v[136:137], v[50:51], v[80:81]
	v_pk_fma_f32 v[86:87], v[78:79], v[50:51], v[86:87] neg_lo:[0,0,1] neg_hi:[0,0,1]
	v_pk_fma_f32 v[50:51], v[206:207], v[50:51], v[52:53]
	s_nop 0
	v_pk_mul_f32 v[52:53], v[136:137], v[50:51]
	v_pk_mul_f32 v[50:51], v[72:73], v[50:51]
	v_pk_fma_f32 v[78:79], v[72:73], v[86:87], v[52:53] neg_lo:[0,0,1] neg_hi:[0,0,1]
	v_pk_mul_f32 v[52:53], v[82:83], v[76:77]
	v_pk_fma_f32 v[72:73], v[136:137], v[86:87], v[50:51]
	v_pk_mul_f32 v[50:51], v[210:211], v[76:77]
	v_pk_fma_f32 v[52:53], v[210:211], v[84:85], v[52:53]
	v_pk_fma_f32 v[50:51], v[82:83], v[84:85], v[50:51] neg_lo:[0,0,1] neg_hi:[0,0,1]
	v_pk_mul_f32 v[84:85], v[70:71], v[52:53]
	v_pk_mul_f32 v[76:77], v[116:117], v[52:53]
	v_pk_fma_f32 v[84:85], v[116:117], v[50:51], v[84:85]
	v_pk_mul_f32 v[86:87], v[210:211], v[52:53]
	v_pk_mul_f32 v[52:53], v[82:83], v[52:53]
	v_pk_fma_f32 v[76:77], v[70:71], v[50:51], v[76:77] neg_lo:[0,0,1] neg_hi:[0,0,1]
	v_pk_fma_f32 v[86:87], v[82:83], v[50:51], v[86:87] neg_lo:[0,0,1] neg_hi:[0,0,1]
	v_pk_fma_f32 v[82:83], v[210:211], v[50:51], v[52:53]
	v_cvt_pk_bf16_f32 v53, v77, v85
	v_cvt_pk_bf16_f32 v52, v76, v84
	v_cvt_pk_bf16_f32 v51, v75, v81
	v_cvt_pk_bf16_f32 v50, v74, v80
	s_nop 1
	v_mfma_f32_16x16x32_bf16 v[62:65], v[46:49], v[50:53], v[62:65]
	v_mul_f32_e64 v52, v70, v82
	v_mul_f32_e64 v53, v71, v83
	v_pk_mul_f32 v[50:51], v[116:117], v[82:83]
	v_pk_fma_f32 v[52:53], v[116:117], v[86:87], v[52:53]
	v_pk_fma_f32 v[50:51], v[70:71], v[86:87], v[50:51] neg_lo:[0,0,1] neg_hi:[0,0,1]
	s_nop 0
	v_cvt_pk_bf16_f32 v53, v51, v53
	v_cvt_pk_bf16_f32 v51, v79, v73
	v_cvt_pk_bf16_f32 v52, v50, v52
	v_cvt_pk_bf16_f32 v50, v78, v72
	s_waitcnt vmcnt(28)
	v_mov_b32_e32 v75, v198
	v_mov_b32_e32 v70, v42
	v_mov_b32_e32 v71, v44
	v_mov_b32_e32 v198, v203
	s_waitcnt vmcnt(24)
	v_mov_b32_e32 v77, v200
	v_mov_b32_e32 v72, v38
	v_mov_b32_e32 v73, v40
	v_mov_b32_e32 v200, v205
	v_mfma_f32_16x16x32_bf16 v[66:69], v[46:49], v[50:53], v[66:69]
	v_mov_b32_e32 v74, v202
	v_mov_b32_e32 v44, v43
	v_pk_mul_f32 v[46:47], v[198:199], v[70:71]
	v_mov_b32_e32 v76, v204
	v_mov_b32_e32 v40, v39
	v_pk_mul_f32 v[48:49], v[200:201], v[72:73]
	v_pk_mul_f32 v[42:43], v[198:199], v[44:45]
	v_pk_fma_f32 v[46:47], v[74:75], v[44:45], v[46:47]
	v_pk_mul_f32 v[38:39], v[200:201], v[40:41]
	v_pk_fma_f32 v[48:49], v[76:77], v[40:41], v[48:49]
	v_pk_fma_f32 v[42:43], v[74:75], v[70:71], v[42:43] neg_lo:[0,0,1] neg_hi:[0,0,1]
	v_pk_fma_f32 v[38:39], v[76:77], v[72:73], v[38:39] neg_lo:[0,0,1] neg_hi:[0,0,1]
	s_nop 0
	v_cvt_pk_bf16_f32 v49, v39, v49
	v_cvt_pk_bf16_f32 v48, v38, v48
	v_cvt_pk_bf16_f32 v47, v43, v47
	v_cvt_pk_bf16_f32 v46, v42, v46
	v_mov_b32_e32 v38, v192
	v_mov_b32_e32 v39, v190
	v_mov_b32_e32 v190, v193
	v_mfma_f32_16x16x32_bf16 v[50:53], v[34:37], v[46:49], v[54:57]
	v_mul_f32_e64 v42, v198, v190
	v_mul_f32_e64 v43, v199, v191
	v_pk_mul_f32 v[46:47], v[198:199], v[38:39]
	v_pk_fma_f32 v[42:43], v[74:75], v[38:39], v[42:43] neg_lo:[0,0,1] neg_hi:[0,0,1]
	v_mov_b32_e32 v56, v196
	s_waitcnt vmcnt(23)
	v_mov_b32_e32 v57, v194
	v_mov_b32_e32 v194, v197
	v_pk_fma_f32 v[54:55], v[74:75], v[190:191], v[46:47]
	v_pk_mul_f32 v[74:75], v[200:201], v[194:195]
	v_pk_mul_f32 v[78:79], v[200:201], v[56:57]
	v_pk_fma_f32 v[74:75], v[76:77], v[56:57], v[74:75] neg_lo:[0,0,1] neg_hi:[0,0,1]
	v_pk_fma_f32 v[76:77], v[76:77], v[194:195], v[78:79]
	v_pk_mul_f32 v[48:49], v[70:71], v[54:55]
	v_pk_mul_f32 v[80:81], v[72:73], v[76:77]
	v_pk_mul_f32 v[46:47], v[44:45], v[54:55]
	v_pk_fma_f32 v[48:49], v[44:45], v[42:43], v[48:49]
	v_pk_mul_f32 v[78:79], v[40:41], v[76:77]
	v_pk_fma_f32 v[80:81], v[40:41], v[74:75], v[80:81]
	v_pk_fma_f32 v[46:47], v[70:71], v[42:43], v[46:47] neg_lo:[0,0,1] neg_hi:[0,0,1]
	v_pk_fma_f32 v[78:79], v[72:73], v[74:75], v[78:79] neg_lo:[0,0,1] neg_hi:[0,0,1]
	v_cvt_pk_bf16_f32 v47, v47, v49
	v_cvt_pk_bf16_f32 v49, v79, v81
	v_cvt_pk_bf16_f32 v46, v46, v48
	v_cvt_pk_bf16_f32 v48, v78, v80
	s_nop 1
	v_mfma_f32_16x16x32_bf16 v[46:49], v[34:37], v[46:49], v[58:61]
	s_nop 2
	v_mul_f32_e64 v58, v190, v54
	v_mul_f32_e64 v59, v191, v55
	v_pk_mul_f32 v[54:55], v[38:39], v[54:55]
	v_pk_fma_f32 v[58:59], v[38:39], v[42:43], v[58:59] neg_lo:[0,0,1] neg_hi:[0,0,1]
	v_pk_fma_f32 v[42:43], v[190:191], v[42:43], v[54:55]
	s_nop 0
	v_pk_mul_f32 v[78:79], v[190:191], v[42:43]
	v_pk_mul_f32 v[54:55], v[44:45], v[42:43]
	v_pk_fma_f32 v[78:79], v[38:39], v[58:59], v[78:79] neg_lo:[0,0,1] neg_hi:[0,0,1]
	v_pk_mul_f32 v[38:39], v[38:39], v[42:43]
	v_pk_mul_f32 v[60:61], v[70:71], v[42:43]
	v_pk_fma_f32 v[38:39], v[190:191], v[58:59], v[38:39]
	v_pk_fma_f32 v[60:61], v[44:45], v[58:59], v[60:61]
	v_pk_mul_f32 v[42:43], v[44:45], v[38:39]
	v_pk_mul_f32 v[38:39], v[70:71], v[38:39]
	v_pk_fma_f32 v[54:55], v[70:71], v[58:59], v[54:55] neg_lo:[0,0,1] neg_hi:[0,0,1]
	v_pk_fma_f32 v[38:39], v[44:45], v[78:79], v[38:39]
	v_pk_mul_f32 v[44:45], v[56:57], v[76:77]
	v_pk_fma_f32 v[58:59], v[70:71], v[78:79], v[42:43] neg_lo:[0,0,1] neg_hi:[0,0,1]
	v_pk_mul_f32 v[42:43], v[194:195], v[76:77]
	v_pk_fma_f32 v[44:45], v[194:195], v[74:75], v[44:45]
	v_pk_fma_f32 v[42:43], v[56:57], v[74:75], v[42:43] neg_lo:[0,0,1] neg_hi:[0,0,1]
	v_pk_mul_f32 v[74:75], v[72:73], v[44:45]
	v_pk_mul_f32 v[70:71], v[40:41], v[44:45]
	v_pk_fma_f32 v[74:75], v[40:41], v[42:43], v[74:75]
	v_pk_mul_f32 v[76:77], v[194:195], v[44:45]
	v_pk_mul_f32 v[44:45], v[56:57], v[44:45]
	v_pk_fma_f32 v[70:71], v[72:73], v[42:43], v[70:71] neg_lo:[0,0,1] neg_hi:[0,0,1]
	v_pk_fma_f32 v[76:77], v[56:57], v[42:43], v[76:77] neg_lo:[0,0,1] neg_hi:[0,0,1]
	v_pk_fma_f32 v[56:57], v[194:195], v[42:43], v[44:45]
	v_cvt_pk_bf16_f32 v45, v71, v75
	v_cvt_pk_bf16_f32 v44, v70, v74
	v_cvt_pk_bf16_f32 v43, v55, v61
	v_cvt_pk_bf16_f32 v42, v54, v60
	v_pk_mul_f32 v[54:55], v[40:41], v[56:57]
	v_pk_mul_f32 v[56:57], v[72:73], v[56:57]
	v_pk_fma_f32 v[54:55], v[72:73], v[76:77], v[54:55] neg_lo:[0,0,1] neg_hi:[0,0,1]
	v_pk_fma_f32 v[40:41], v[40:41], v[76:77], v[56:57]
	v_cvt_pk_bf16_f32 v38, v58, v38
	v_cvt_pk_bf16_f32 v41, v55, v41
	v_cvt_pk_bf16_f32 v40, v54, v40
	v_cvt_pk_bf16_f32 v39, v59, v39
	s_waitcnt vmcnt(17)
	v_mov_b32_e32 v59, v182
	v_mov_b32_e32 v55, v32
	v_mov_b32_e32 v182, v185
	v_mov_b32_e32 v32, v31
	v_mov_b32_e32 v58, v184
	v_mov_b32_e32 v54, v30
	v_pk_mul_f32 v[30:31], v[182:183], v[32:33]
	v_mfma_f32_16x16x32_bf16 v[42:45], v[34:37], v[42:45], v[62:65]
	s_waitcnt vmcnt(13)
	v_mov_b32_e32 v57, v176
	v_mov_b32_e32 v176, v187
	v_mov_b32_e32 v56, v186
	v_mfma_f32_16x16x32_bf16 v[34:37], v[34:37], v[38:41], v[66:69]
	v_fma_f32 v38, v58, v54, -v30
	v_fma_f32 v39, v59, v55, -v31
	v_pk_mul_f32 v[30:31], v[182:183], v[54:55]
	s_nop 0
	v_pk_fma_f32 v[40:41], v[58:59], v[32:33], v[30:31]
	v_mov_b32_e32 v30, v22
	v_mov_b32_e32 v31, v24
	v_mov_b32_e32 v24, v23
	v_pk_mul_f32 v[60:61], v[176:177], v[30:31]
	v_pk_mul_f32 v[22:23], v[176:177], v[24:25]
	v_pk_fma_f32 v[60:61], v[56:57], v[24:25], v[60:61]
	v_pk_fma_f32 v[22:23], v[56:57], v[30:31], v[22:23] neg_lo:[0,0,1] neg_hi:[0,0,1]
	v_cvt_pk_bf16_f32 v39, v39, v41
	v_cvt_pk_bf16_f32 v41, v23, v61
	v_cvt_pk_bf16_f32 v38, v38, v40
	v_cvt_pk_bf16_f32 v40, v22, v60
	s_nop 1
	v_mfma_f32_16x16x32_bf16 v[38:41], v[14:17], v[38:41], v[50:53]
	s_nop 2
	v_mov_b32_e32 v51, v172
	v_mov_b32_e32 v172, v179
	v_mov_b32_e32 v50, v178
	v_pk_mul_f32 v[22:23], v[182:183], v[172:173]
	s_nop 0
	v_pk_fma_f32 v[52:53], v[58:59], v[50:51], v[22:23] neg_lo:[0,0,1] neg_hi:[0,0,1]
	v_pk_mul_f32 v[22:23], v[182:183], v[50:51]
	s_nop 0
	v_pk_fma_f32 v[58:59], v[58:59], v[172:173], v[22:23]
	s_nop 0
	v_pk_mul_f32 v[22:23], v[32:33], v[58:59]
	s_nop 0
	v_pk_fma_f32 v[60:61], v[54:55], v[52:53], v[22:23] neg_lo:[0,0,1] neg_hi:[0,0,1]
	v_pk_mul_f32 v[22:23], v[54:55], v[58:59]
	s_nop 0
	v_pk_fma_f32 v[62:63], v[32:33], v[52:53], v[22:23]
	v_mov_b32_e32 v22, v180
	s_waitcnt vmcnt(12)
	v_mov_b32_e32 v23, v170
	v_mov_b32_e32 v170, v181
	v_pk_mul_f32 v[64:65], v[176:177], v[170:171]
	v_pk_mul_f32 v[66:67], v[176:177], v[22:23]
	v_pk_fma_f32 v[64:65], v[56:57], v[22:23], v[64:65] neg_lo:[0,0,1] neg_hi:[0,0,1]
	v_pk_fma_f32 v[56:57], v[56:57], v[170:171], v[66:67]
	s_nop 0
	v_pk_mul_f32 v[68:69], v[30:31], v[56:57]
	v_pk_mul_f32 v[66:67], v[24:25], v[56:57]
	v_pk_fma_f32 v[68:69], v[24:25], v[64:65], v[68:69]
	v_pk_fma_f32 v[66:67], v[30:31], v[64:65], v[66:67] neg_lo:[0,0,1] neg_hi:[0,0,1]
	v_cvt_pk_bf16_f32 v61, v61, v63
	v_cvt_pk_bf16_f32 v63, v67, v69
	v_cvt_pk_bf16_f32 v60, v60, v62
	v_cvt_pk_bf16_f32 v62, v66, v68
	s_nop 1
	v_mfma_f32_16x16x32_bf16 v[46:49], v[14:17], v[60:63], v[46:49]
	v_mul_f32_e64 v60, v172, v58
	v_mul_f32_e64 v61, v173, v59
	v_pk_mul_f32 v[58:59], v[50:51], v[58:59]
	v_pk_fma_f32 v[60:61], v[50:51], v[52:53], v[60:61] neg_lo:[0,0,1] neg_hi:[0,0,1]
	v_pk_fma_f32 v[52:53], v[172:173], v[52:53], v[58:59]
	s_nop 0
	v_pk_mul_f32 v[66:67], v[172:173], v[52:53]
	v_pk_mul_f32 v[58:59], v[32:33], v[52:53]
	v_pk_fma_f32 v[66:67], v[50:51], v[60:61], v[66:67] neg_lo:[0,0,1] neg_hi:[0,0,1]
	v_pk_mul_f32 v[50:51], v[50:51], v[52:53]
	v_pk_mul_f32 v[62:63], v[54:55], v[52:53]
	v_pk_fma_f32 v[50:51], v[172:173], v[60:61], v[50:51]
	v_pk_fma_f32 v[58:59], v[54:55], v[60:61], v[58:59] neg_lo:[0,0,1] neg_hi:[0,0,1]
	v_pk_mul_f32 v[52:53], v[32:33], v[50:51]
	v_pk_fma_f32 v[62:63], v[32:33], v[60:61], v[62:63]
	v_pk_fma_f32 v[60:61], v[54:55], v[66:67], v[52:53] neg_lo:[0,0,1] neg_hi:[0,0,1]
	v_pk_mul_f32 v[50:51], v[54:55], v[50:51]
	v_pk_mul_f32 v[52:53], v[22:23], v[56:57]
	v_pk_fma_f32 v[32:33], v[32:33], v[66:67], v[50:51]
	v_pk_mul_f32 v[50:51], v[170:171], v[56:57]
	v_pk_fma_f32 v[52:53], v[170:171], v[64:65], v[52:53]
	v_pk_fma_f32 v[50:51], v[22:23], v[64:65], v[50:51] neg_lo:[0,0,1] neg_hi:[0,0,1]
	v_pk_mul_f32 v[56:57], v[30:31], v[52:53]
	v_pk_mul_f32 v[64:65], v[170:171], v[52:53]
	v_pk_mul_f32 v[54:55], v[24:25], v[52:53]
	v_pk_fma_f32 v[56:57], v[24:25], v[50:51], v[56:57]
	v_pk_fma_f32 v[64:65], v[22:23], v[50:51], v[64:65] neg_lo:[0,0,1] neg_hi:[0,0,1]
	v_pk_mul_f32 v[22:23], v[22:23], v[52:53]
	v_pk_fma_f32 v[54:55], v[30:31], v[50:51], v[54:55] neg_lo:[0,0,1] neg_hi:[0,0,1]
	v_pk_fma_f32 v[22:23], v[170:171], v[50:51], v[22:23]
	v_cvt_pk_bf16_f32 v53, v55, v57
	v_cvt_pk_bf16_f32 v52, v54, v56
	v_cvt_pk_bf16_f32 v51, v59, v63
	v_cvt_pk_bf16_f32 v50, v58, v62
	s_nop 1
	v_mfma_f32_16x16x32_bf16 v[42:45], v[14:17], v[50:53], v[42:45]
	v_mul_f32_e64 v50, v24, v22
	v_mul_f32_e64 v51, v25, v23
	v_pk_mul_f32 v[22:23], v[30:31], v[22:23]
	v_pk_fma_f32 v[50:51], v[30:31], v[64:65], v[50:51] neg_lo:[0,0,1] neg_hi:[0,0,1]
	v_pk_fma_f32 v[22:23], v[24:25], v[64:65], v[22:23]
	s_nop 0
	v_cvt_pk_bf16_f32 v25, v51, v23
	v_cvt_pk_bf16_f32 v23, v61, v33
	v_cvt_pk_bf16_f32 v24, v50, v22
	v_cvt_pk_bf16_f32 v22, v60, v32
	s_waitcnt vmcnt(7)
	v_mov_b32_e32 v50, v26
	v_mov_b32_e32 v51, v28
	v_mfma_f32_16x16x32_bf16 v[34:37], v[14:17], v[22:25], v[34:37]
	s_waitcnt vmcnt(6)
	v_mov_b32_e32 v23, v164
	v_mov_b32_e32 v164, v163
	v_mov_b32_e32 v28, v27
	s_waitcnt vmcnt(4)
	v_mov_b32_e32 v25, v174
	v_mov_b32_e32 v26, v18
	v_mov_b32_e32 v27, v20
	s_waitcnt vmcnt(3)
	v_mov_b32_e32 v174, v169
	v_mov_b32_e32 v22, v162
	v_pk_mul_f32 v[16:17], v[164:165], v[50:51]
	v_mov_b32_e32 v24, v168
	v_mov_b32_e32 v20, v19
	v_pk_mul_f32 v[30:31], v[174:175], v[26:27]
	v_pk_mul_f32 v[14:15], v[164:165], v[28:29]
	v_pk_fma_f32 v[16:17], v[22:23], v[28:29], v[16:17]
	v_pk_mul_f32 v[18:19], v[174:175], v[20:21]
	v_pk_fma_f32 v[30:31], v[24:25], v[20:21], v[30:31]
	v_pk_fma_f32 v[14:15], v[22:23], v[50:51], v[14:15] neg_lo:[0,0,1] neg_hi:[0,0,1]
	v_pk_fma_f32 v[18:19], v[24:25], v[26:27], v[18:19] neg_lo:[0,0,1] neg_hi:[0,0,1]
	v_cvt_pk_bf16_f32 v15, v15, v17
	v_cvt_pk_bf16_f32 v17, v19, v31
	v_cvt_pk_bf16_f32 v14, v14, v16
	v_cvt_pk_bf16_f32 v16, v18, v30
	v_mov_b32_e32 v19, v158
	v_mov_b32_e32 v158, v161
	v_mfma_f32_16x16x32_bf16 v[30:33], v[10:13], v[14:17], v[38:41]
	v_mov_b32_e32 v18, v160
	v_pk_mul_f32 v[14:15], v[164:165], v[158:159]
	s_waitcnt vmcnt(1)
	v_mov_b32_e32 v53, v188
	v_pk_fma_f32 v[38:39], v[22:23], v[18:19], v[14:15] neg_lo:[0,0,1] neg_hi:[0,0,1]
	v_pk_mul_f32 v[14:15], v[164:165], v[18:19]
	v_mov_b32_e32 v188, v167
	v_pk_fma_f32 v[40:41], v[22:23], v[158:159], v[14:15]
	v_mov_b32_e32 v52, v166
	v_pk_mul_f32 v[22:23], v[174:175], v[188:189]
	v_pk_mul_f32 v[16:17], v[50:51], v[40:41]
	v_pk_fma_f32 v[54:55], v[24:25], v[52:53], v[22:23] neg_lo:[0,0,1] neg_hi:[0,0,1]
	v_pk_mul_f32 v[22:23], v[174:175], v[52:53]
	v_pk_mul_f32 v[14:15], v[28:29], v[40:41]
	v_pk_fma_f32 v[56:57], v[24:25], v[188:189], v[22:23]
	v_pk_fma_f32 v[16:17], v[28:29], v[38:39], v[16:17]
	v_pk_mul_f32 v[24:25], v[26:27], v[56:57]
	v_pk_mul_f32 v[22:23], v[20:21], v[56:57]
	v_pk_fma_f32 v[24:25], v[20:21], v[54:55], v[24:25]
	v_pk_fma_f32 v[14:15], v[50:51], v[38:39], v[14:15] neg_lo:[0,0,1] neg_hi:[0,0,1]
	v_pk_fma_f32 v[22:23], v[26:27], v[54:55], v[22:23] neg_lo:[0,0,1] neg_hi:[0,0,1]
	v_cvt_pk_bf16_f32 v15, v15, v17
	v_cvt_pk_bf16_f32 v17, v23, v25
	v_cvt_pk_bf16_f32 v14, v14, v16
	v_cvt_pk_bf16_f32 v16, v22, v24
	s_nop 1
	v_mfma_f32_16x16x32_bf16 v[22:25], v[10:13], v[14:17], v[46:49]
	v_mul_f32_e64 v16, v18, v40
	v_mul_f32_e64 v17, v19, v41
	v_pk_mul_f32 v[14:15], v[158:159], v[40:41]
	v_pk_fma_f32 v[16:17], v[158:159], v[38:39], v[16:17]
	v_pk_fma_f32 v[14:15], v[18:19], v[38:39], v[14:15] neg_lo:[0,0,1] neg_hi:[0,0,1]
	v_pk_mul_f32 v[38:39], v[28:29], v[16:17]
	v_pk_mul_f32 v[40:41], v[50:51], v[16:17]
	v_pk_mul_f32 v[46:47], v[158:159], v[16:17]
	v_pk_mul_f32 v[16:17], v[18:19], v[16:17]
	v_pk_fma_f32 v[38:39], v[50:51], v[14:15], v[38:39] neg_lo:[0,0,1] neg_hi:[0,0,1]
	v_pk_fma_f32 v[40:41], v[28:29], v[14:15], v[40:41]
	v_pk_fma_f32 v[46:47], v[18:19], v[14:15], v[46:47] neg_lo:[0,0,1] neg_hi:[0,0,1]
	v_pk_fma_f32 v[14:15], v[158:159], v[14:15], v[16:17]
	s_nop 0
	v_pk_mul_f32 v[16:17], v[28:29], v[14:15]
	v_pk_mul_f32 v[14:15], v[50:51], v[14:15]
	v_pk_fma_f32 v[18:19], v[50:51], v[46:47], v[16:17] neg_lo:[0,0,1] neg_hi:[0,0,1]
	v_pk_mul_f32 v[16:17], v[52:53], v[56:57]
	v_pk_fma_f32 v[28:29], v[28:29], v[46:47], v[14:15]
	v_pk_mul_f32 v[14:15], v[188:189], v[56:57]
	v_pk_fma_f32 v[16:17], v[188:189], v[54:55], v[16:17]
	v_pk_fma_f32 v[14:15], v[52:53], v[54:55], v[14:15] neg_lo:[0,0,1] neg_hi:[0,0,1]
	v_pk_mul_f32 v[48:49], v[26:27], v[16:17]
	v_pk_mul_f32 v[46:47], v[20:21], v[16:17]
	v_pk_fma_f32 v[48:49], v[20:21], v[14:15], v[48:49]
	v_pk_mul_f32 v[50:51], v[188:189], v[16:17]
	v_pk_mul_f32 v[16:17], v[52:53], v[16:17]
	v_pk_fma_f32 v[46:47], v[26:27], v[14:15], v[46:47] neg_lo:[0,0,1] neg_hi:[0,0,1]
	v_pk_fma_f32 v[50:51], v[52:53], v[14:15], v[50:51] neg_lo:[0,0,1] neg_hi:[0,0,1]
	v_pk_fma_f32 v[52:53], v[188:189], v[14:15], v[16:17]
	v_cvt_pk_bf16_f32 v17, v47, v49
	v_cvt_pk_bf16_f32 v16, v46, v48
	v_cvt_pk_bf16_f32 v15, v39, v41
	v_cvt_pk_bf16_f32 v14, v38, v40
	v_pk_mul_f32 v[38:39], v[20:21], v[52:53]
	s_nop 0
	v_pk_fma_f32 v[38:39], v[26:27], v[50:51], v[38:39] neg_lo:[0,0,1] neg_hi:[0,0,1]
	v_pk_mul_f32 v[26:27], v[26:27], v[52:53]
	s_nop 0
	v_pk_fma_f32 v[20:21], v[20:21], v[50:51], v[26:27]
	v_cvt_pk_bf16_f32 v19, v19, v29
	v_cvt_pk_bf16_f32 v18, v18, v28
	v_cvt_pk_bf16_f32 v21, v39, v21
	v_cvt_pk_bf16_f32 v20, v38, v20
	v_mfma_f32_16x16x32_bf16 v[14:17], v[10:13], v[14:17], v[42:45]
	v_mov_b32_e32 v29, v32
	v_mov_b32_e32 v32, v31
	v_mov_b32_e32 v28, v30
	v_mfma_f32_16x16x32_bf16 v[10:13], v[10:13], v[18:21], v[34:37]
	s_waitcnt vmcnt(0)
	v_mov_b32_e32 v19, v8
	v_mov_b32_e32 v8, v7
	v_mov_b32_e32 v18, v6
	v_add_u32_e32 v34, s22, v242
	ds_read_b64 v[20:21], v34
	v_add_u32_e32 v242, 32, v242
	s_waitcnt lgkmcnt(0)
	v_lshlrev_b32_e32 v27, 16, v21
	v_lshlrev_b32_e32 v26, 16, v20
	v_and_b32_e32 v21, 0xffff0000, v21
	v_and_b32_e32 v20, 0xffff0000, v20
	v_pk_fma_f32 v[20:21], v[8:9], v[20:21], v[32:33]
	v_pk_fma_f32 v[26:27], v[18:19], v[26:27], v[28:29]
	v_mul_f32_e32 v7, 0x3d372713, v20
	v_mul_f32_e32 v7, v20, v7
	v_fma_f32 v7, v20, v7, v20
	v_mul_f32_e32 v7, 0x3f4c422a, v7
	v_mul_f32_e32 v7, -2.0, v7
	v_mul_f32_e32 v7, 0x3fb8aa3b, v7
	v_exp_f32_e32 v7, v7
	v_mul_f32_e32 v6, 0x3d372713, v26
	v_mul_f32_e32 v6, v26, v6
	v_fma_f32 v6, v26, v6, v26
	v_add_f32_e32 v7, 1.0, v7
	v_rcp_f32_e32 v28, v7
	v_mul_f32_e32 v7, 0x3d372713, v27
	v_mul_f32_e32 v7, v27, v7
	v_fma_f32 v7, v27, v7, v27
	v_mul_f32_e32 v6, 0x3f4c422a, v6
	v_mul_f32_e32 v7, 0x3f4c422a, v7
	v_mul_f32_e32 v6, -2.0, v6
	v_mul_f32_e32 v7, -2.0, v7
	v_mul_f32_e32 v6, 0x3fb8aa3b, v6
	v_mul_f32_e32 v7, 0x3fb8aa3b, v7
	v_exp_f32_e32 v6, v6
	v_exp_f32_e32 v7, v7
	v_add_f32_e32 v6, 1.0, v6
	v_add_f32_e32 v7, 1.0, v7
	v_rcp_f32_e32 v6, v6
	v_rcp_f32_e32 v7, v7
	s_nop 0
	v_pk_mul_f32 v[6:7], v[26:27], v[6:7]
	v_mul_f32_e32 v26, 0x3d372713, v21
	v_mul_f32_e32 v26, v21, v26
	v_fma_f32 v26, v21, v26, v21
	v_mul_f32_e32 v26, 0x3f4c422a, v26
	v_mul_f32_e32 v26, -2.0, v26
	v_mul_f32_e32 v26, 0x3fb8aa3b, v26
	v_exp_f32_e32 v26, v26
	s_nop 0
	v_add_f32_e32 v26, 1.0, v26
	v_rcp_f32_e32 v29, v26
	s_nop 0
	v_pk_mul_f32 v[20:21], v[20:21], v[28:29]
	s_nop 0
	v_cvt_pk_bf16_f32 v6, v6, v20
	v_cvt_pk_bf16_f32 v7, v7, v21
	ds_write_b64 v34, v[6:7]
	v_add_u32_e32 v28, s22, v241
	ds_read_b64 v[6:7], v28 offset:33280
	v_mov_b32_e32 v27, v24
	v_mov_b32_e32 v24, v23
	v_mov_b32_e32 v26, v22
	v_add_u32_e32 v241, 32, v241
	s_waitcnt lgkmcnt(0)
	v_lshlrev_b32_e32 v21, 16, v7
	v_lshlrev_b32_e32 v20, 16, v6
	v_and_b32_e32 v7, 0xffff0000, v7
	v_and_b32_e32 v6, 0xffff0000, v6
	v_pk_fma_f32 v[6:7], v[8:9], v[6:7], v[24:25]
	v_pk_fma_f32 v[20:21], v[18:19], v[20:21], v[26:27]
	v_mul_f32_e32 v23, 0x3d372713, v6
	v_mul_f32_e32 v23, v6, v23
	v_fma_f32 v23, v6, v23, v6
	v_mul_f32_e32 v23, 0x3f4c422a, v23
	v_mul_f32_e32 v23, -2.0, v23
	v_mul_f32_e32 v23, 0x3fb8aa3b, v23
	v_exp_f32_e32 v23, v23
	v_mul_f32_e32 v22, 0x3d372713, v20
	v_mul_f32_e32 v22, v20, v22
	v_fma_f32 v22, v20, v22, v20
	v_add_f32_e32 v23, 1.0, v23
	v_rcp_f32_e32 v24, v23
	v_mul_f32_e32 v23, 0x3d372713, v21
	v_mul_f32_e32 v23, v21, v23
	v_fma_f32 v23, v21, v23, v21
	v_mul_f32_e32 v22, 0x3f4c422a, v22
	v_mul_f32_e32 v23, 0x3f4c422a, v23
	v_mul_f32_e32 v22, -2.0, v22
	v_mul_f32_e32 v23, -2.0, v23
	v_mul_f32_e32 v22, 0x3fb8aa3b, v22
	v_mul_f32_e32 v23, 0x3fb8aa3b, v23
	v_exp_f32_e32 v22, v22
	v_exp_f32_e32 v23, v23
	v_add_f32_e32 v22, 1.0, v22
	v_add_f32_e32 v23, 1.0, v23
	v_rcp_f32_e32 v22, v22
	v_rcp_f32_e32 v23, v23
	s_nop 0
	v_pk_mul_f32 v[20:21], v[20:21], v[22:23]
	v_mul_f32_e32 v22, 0x3d372713, v7
	v_mul_f32_e32 v22, v7, v22
	v_fma_f32 v22, v7, v22, v7
	v_mul_f32_e32 v22, 0x3f4c422a, v22
	v_mul_f32_e32 v22, -2.0, v22
	v_mul_f32_e32 v22, 0x3fb8aa3b, v22
	v_exp_f32_e32 v22, v22
	s_nop 0
	v_add_f32_e32 v22, 1.0, v22
	v_rcp_f32_e32 v25, v22
	s_nop 0
	v_pk_mul_f32 v[6:7], v[6:7], v[24:25]
	s_nop 0
	v_cvt_pk_bf16_f32 v6, v20, v6
	v_cvt_pk_bf16_f32 v7, v21, v7
	ds_write_b64 v28, v[6:7] offset:33280
	ds_read_b64 v[6:7], v28 offset:49920
	v_mov_b32_e32 v23, v16
	v_mov_b32_e32 v16, v15
	v_mov_b32_e32 v22, v14
	s_waitcnt lgkmcnt(0)
	v_lshlrev_b32_e32 v21, 16, v7
	v_lshlrev_b32_e32 v20, 16, v6
	v_and_b32_e32 v7, 0xffff0000, v7
	v_and_b32_e32 v6, 0xffff0000, v6
	v_pk_fma_f32 v[6:7], v[8:9], v[6:7], v[16:17]
	v_pk_fma_f32 v[20:21], v[18:19], v[20:21], v[22:23]
	v_mul_f32_e32 v15, 0x3d372713, v6
	v_mul_f32_e32 v15, v6, v15
	v_fma_f32 v15, v6, v15, v6
	v_mul_f32_e32 v15, 0x3f4c422a, v15
	v_mul_f32_e32 v15, -2.0, v15
	v_mul_f32_e32 v15, 0x3fb8aa3b, v15
	v_exp_f32_e32 v15, v15
	v_mul_f32_e32 v14, 0x3d372713, v20
	v_mul_f32_e32 v14, v20, v14
	v_mul_f32_e32 v17, 0x3d372713, v7
	v_add_f32_e32 v15, 1.0, v15
	v_rcp_f32_e32 v16, v15
	v_mul_f32_e32 v15, 0x3d372713, v21
	v_mul_f32_e32 v15, v21, v15
	v_fma_f32 v14, v20, v14, v20
	v_fma_f32 v15, v21, v15, v21
	v_mul_f32_e32 v17, v7, v17
	v_mul_f32_e32 v14, 0x3f4c422a, v14
	v_mul_f32_e32 v15, 0x3f4c422a, v15
	v_fma_f32 v17, v7, v17, v7
	v_mul_f32_e32 v14, -2.0, v14
	v_mul_f32_e32 v15, -2.0, v15
	v_mul_f32_e32 v17, 0x3f4c422a, v17
	v_mul_f32_e32 v14, 0x3fb8aa3b, v14
	v_mul_f32_e32 v15, 0x3fb8aa3b, v15
	v_mul_f32_e32 v17, -2.0, v17
	v_exp_f32_e32 v14, v14
	v_exp_f32_e32 v15, v15
	v_mul_f32_e32 v17, 0x3fb8aa3b, v17
	v_exp_f32_e32 v17, v17
	v_add_f32_e32 v14, 1.0, v14
	v_add_f32_e32 v15, 1.0, v15
	v_rcp_f32_e32 v14, v14
	v_rcp_f32_e32 v15, v15
	v_add_f32_e32 v17, 1.0, v17
	v_rcp_f32_e32 v17, v17
	v_pk_mul_f32 v[14:15], v[20:21], v[14:15]
	v_add_u32_e32 v20, 0x10400, v28
	v_pk_mul_f32 v[6:7], v[6:7], v[16:17]
	s_nop 0
	v_cvt_pk_bf16_f32 v7, v15, v7
	v_cvt_pk_bf16_f32 v6, v14, v6
	ds_write_b64 v28, v[6:7] offset:49920
	ds_read_b64 v[6:7], v20
	v_mov_b32_e32 v16, v10
	v_mov_b32_e32 v17, v12
	v_mov_b32_e32 v12, v11
	s_waitcnt lgkmcnt(0)
	v_lshlrev_b32_e32 v15, 16, v7
	v_lshlrev_b32_e32 v14, 16, v6
	v_pk_fma_f32 v[14:15], v[18:19], v[14:15], v[16:17]
	v_and_b32_e32 v7, 0xffff0000, v7
	v_and_b32_e32 v6, 0xffff0000, v6
	v_pk_fma_f32 v[6:7], v[8:9], v[6:7], v[12:13]
	v_mul_f32_e32 v9, 0x3d372713, v15
	v_mul_f32_e32 v9, v15, v9
	v_fma_f32 v9, v15, v9, v15
	v_mul_f32_e32 v9, 0x3f4c422a, v9
	v_mul_f32_e32 v9, -2.0, v9
	v_mul_f32_e32 v9, 0x3fb8aa3b, v9
	v_exp_f32_e32 v9, v9
	v_mul_f32_e32 v10, 0x3d372713, v14
	v_mul_f32_e32 v10, v14, v10
	v_mul_f32_e32 v8, 0x3d372713, v6
	v_add_f32_e32 v9, 1.0, v9
	v_rcp_f32_e32 v11, v9
	v_mul_f32_e32 v9, 0x3d372713, v7
	v_fma_f32 v10, v14, v10, v14
	v_mul_f32_e32 v8, v6, v8
	v_mul_f32_e32 v9, v7, v9
	v_mul_f32_e32 v10, 0x3f4c422a, v10
	v_fma_f32 v8, v6, v8, v6
	v_fma_f32 v9, v7, v9, v7
	v_mul_f32_e32 v10, -2.0, v10
	v_mul_f32_e32 v8, 0x3f4c422a, v8
	v_mul_f32_e32 v9, 0x3f4c422a, v9
	v_mul_f32_e32 v10, 0x3fb8aa3b, v10
	v_mul_f32_e32 v8, -2.0, v8
	v_mul_f32_e32 v9, -2.0, v9
	v_exp_f32_e32 v10, v10
	v_mul_f32_e32 v8, 0x3fb8aa3b, v8
	v_mul_f32_e32 v9, 0x3fb8aa3b, v9
	v_exp_f32_e32 v8, v8
	v_exp_f32_e32 v9, v9
	v_add_f32_e32 v10, 1.0, v10
	v_rcp_f32_e32 v10, v10
	v_add_f32_e32 v8, 1.0, v8
	v_add_f32_e32 v9, 1.0, v9
	v_rcp_f32_e32 v8, v8
	v_rcp_f32_e32 v9, v9
	v_pk_mul_f32 v[10:11], v[14:15], v[10:11]
	v_pk_mul_f32 v[6:7], v[6:7], v[8:9]
	s_nop 0
	v_cvt_pk_bf16_f32 v7, v11, v7
	v_cvt_pk_bf16_f32 v6, v10, v6
	ds_write_b64 v20, v[6:7]
	s_cbranch_scc0 .LBB0_464
	s_and_b32 s0, s20, 0xffffffc0
	v_or_b32_e32 v6, s0, v1
	v_ashrrev_i32_e32 v7, 31, v6
	v_readlane_b32 s4, v254, 8
	v_lshlrev_b64 v[10:11], 10, v[6:7]
	v_readlane_b32 s5, v254, 9
	s_ashr_i32 s1, s0, 31
	v_readlane_b32 s6, v254, 10
	v_lshl_add_u64 v[6:7], s[4:5], 0, v[10:11]
	s_nop 1
	s_mov_b64 s[36:37], s[4:5]
	s_add_u32 s38, s4, 0x4000
	s_addc_u32 s39, s5, 0
	s_add_u32 s40, s4, 0x8000
	s_addc_u32 s41, s5, 0
	s_add_u32 s44, s4, 0xc000
	s_addc_u32 s45, s5, 0
	s_lshl_b64 s[4:5], s[0:1], 2
	s_add_u32 s4, s6, s4
	v_readlane_b32 s6, v254, 11
	s_addc_u32 s5, s6, s5
	v_readlane_b32 s6, v251, 55
	v_lshlrev_b32_e32 v12, 1, v238
	v_add_u32_e32 v239, v10, v12
	v_mov_b32_e32 v13, v139
	v_readlane_b32 s7, v251, 56
	v_lshl_add_u64 v[136:137], v[6:7], 0, v[12:13]
	v_or_b32_e32 v22, s88, v1
	v_mov_b64_e32 v[6:7], s[6:7]
	s_movk_i32 s10, 0x2800
	v_mad_i64_i32 v[134:135], s[6:7], v22, s10, v[6:7]
	s_lshl_b64 s[6:7], s[0:1], 1
	s_nop 0
	v_lshl_add_u64 v[8:9], v[134:135], 0, s[6:7]
	v_lshlrev_b32_e32 v14, 1, v146
	v_mov_b32_e32 v15, v139
	v_lshl_add_u64 v[16:17], v[8:9], 0, v[14:15]
	v_or_b32_e32 v8, 16, v22
	v_mad_i64_i32 v[8:9], s[8:9], v8, s10, v[6:7]
	v_lshl_add_u64 v[8:9], v[8:9], 0, s[6:7]
	v_lshl_add_u64 v[18:19], v[8:9], 0, v[14:15]
	v_or_b32_e32 v8, 32, v22
	v_mad_i64_i32 v[8:9], s[8:9], v8, s10, v[6:7]
	v_lshl_add_u64 v[8:9], v[8:9], 0, s[6:7]
	v_lshl_add_u64 v[20:21], v[8:9], 0, v[14:15]
	v_or_b32_e32 v8, 48, v22
	v_mad_i64_i32 v[6:7], s[8:9], v8, s10, v[6:7]
	v_lshl_add_u64 v[6:7], v[6:7], 0, s[6:7]
	v_lshl_add_u64 v[14:15], v[6:7], 0, v[14:15]
	v_add_co_u32_e32 v6, vcc, s69, v136
	v_lshlrev_b32_e32 v13, 2, v146
	s_nop 0
	v_addc_co_u32_e32 v7, vcc, 0, v137, vcc
	v_add_co_u32_e32 v8, vcc, s19, v136
	global_load_dwordx4 v[74:77], v[136:137], off
	s_nop 0
	v_addc_co_u32_e32 v9, vcc, 0, v137, vcc
	global_load_dwordx4 v[66:69], v13, s[4:5]
	global_load_dwordx4 v[46:49], v13, s[4:5] offset:64
	global_load_dwordx4 v[96:99], v[6:7], off
	global_load_dwordx4 v[92:95], v[8:9], off
	v_add_co_u32_e32 v6, vcc, s27, v136
	v_add_u32_e32 v150, 0, v237
	s_nop 0
	v_addc_co_u32_e32 v7, vcc, 0, v137, vcc
	global_load_dwordx4 v[88:91], v[6:7], off
	global_load_dwordx4 v[26:29], v13, s[4:5] offset:128
	s_nop 0
	global_load_dwordx4 v[6:9], v13, s[4:5] offset:192
	global_load_dwordx4 v[140:143], v239, s[36:37] offset:64
	global_load_dwordx4 v[152:155], v239, s[38:39] offset:64
	global_load_dwordx4 v[156:159], v239, s[40:41] offset:64
	global_load_dwordx4 v[160:163], v239, s[44:45] offset:64
	global_load_dwordx4 v[180:183], v239, s[36:37] offset:128
	global_load_dwordx4 v[184:187], v239, s[38:39] offset:128
	global_load_dwordx4 v[188:191], v239, s[40:41] offset:128
	global_load_dwordx4 v[192:195], v239, s[44:45] offset:128
	global_load_dwordx4 v[196:199], v239, s[36:37] offset:192
	global_load_dwordx4 v[200:203], v239, s[38:39] offset:192
	global_load_dwordx4 v[204:207], v239, s[40:41] offset:192
	global_load_dwordx4 v[208:211], v239, s[44:45] offset:192
	global_load_dwordx4 v[212:215], v239, s[36:37] offset:256
	global_load_dwordx4 v[216:219], v239, s[38:39] offset:256
	global_load_dwordx4 v[240:243], v239, s[40:41] offset:256
	global_load_dwordx4 v[244:247], v239, s[44:45] offset:256
	global_load_dwordx2 v[78:79], v[16:17], off offset:2560
	global_load_dwordx2 v[126:127], v[16:17], off offset:2592
	global_load_dwordx2 v[118:119], v[16:17], off offset:2624
	global_load_dwordx2 v[110:111], v[16:17], off offset:2656
	global_load_dwordx2 v[132:133], v[18:19], off offset:2560
	global_load_dwordx2 v[124:125], v[18:19], off offset:2592
	global_load_dwordx2 v[116:117], v[18:19], off offset:2624
	global_load_dwordx2 v[108:109], v[18:19], off offset:2656
	global_load_dwordx2 v[130:131], v[20:21], off offset:2560
	global_load_dwordx2 v[122:123], v[20:21], off offset:2592
	global_load_dwordx2 v[114:115], v[20:21], off offset:2624
	global_load_dwordx2 v[106:107], v[20:21], off offset:2656
	global_load_dwordx2 v[128:129], v[14:15], off offset:2560
	global_load_dwordx2 v[120:121], v[14:15], off offset:2592
	global_load_dwordx2 v[112:113], v[14:15], off offset:2624
	global_load_dwordx2 v[104:105], v[14:15], off offset:2656
	v_readlane_b32 s4, v254, 61
	v_or_b32_e32 v10, v10, v138
	v_readlane_b32 s5, v254, 62
	v_mov_b32_e32 v30, 0
	v_add_u32_e32 v151, v150, v12
	v_lshl_add_u64 v[148:149], s[4:5], 0, v[10:11]
	s_mov_b64 s[22:23], 0
	s_mov_b32 s1, 64
	v_mov_b32_e32 v31, v30
	v_mov_b32_e32 v32, v30
	v_mov_b32_e32 v33, v30
	v_mov_b32_e32 v34, v30
	v_mov_b32_e32 v35, v30
	v_mov_b32_e32 v36, v30
	v_mov_b32_e32 v37, v30
	v_mov_b32_e32 v38, v30
	v_mov_b32_e32 v39, v30
	v_mov_b32_e32 v40, v30
	v_mov_b32_e32 v41, v30
	v_mov_b32_e32 v42, v30
	v_mov_b32_e32 v43, v30
	v_mov_b32_e32 v44, v30
	v_mov_b32_e32 v45, v30
	v_mov_b32_e32 v50, v30
	v_mov_b32_e32 v51, v30
	v_mov_b32_e32 v52, v30
	v_mov_b32_e32 v53, v30
	v_mov_b32_e32 v54, v30
	v_mov_b32_e32 v55, v30
	v_mov_b32_e32 v56, v30
	v_mov_b32_e32 v57, v30
	v_mov_b32_e32 v58, v30
	v_mov_b32_e32 v59, v30
	v_mov_b32_e32 v60, v30
	v_mov_b32_e32 v61, v30
	v_mov_b32_e32 v62, v30
	v_mov_b32_e32 v63, v30
	v_mov_b32_e32 v64, v30
	v_mov_b32_e32 v65, v30
	v_mov_b32_e32 v70, v30
	v_mov_b32_e32 v71, v30
	v_mov_b32_e32 v72, v30
	v_mov_b32_e32 v73, v30
	v_mov_b32_e32 v84, v30
	v_mov_b32_e32 v85, v30
	v_mov_b32_e32 v86, v30
	v_mov_b32_e32 v87, v30
	v_mov_b32_e32 v80, v30
	v_mov_b32_e32 v81, v30
	v_mov_b32_e32 v82, v30
	v_mov_b32_e32 v83, v30
	v_mov_b32_e32 v100, v30
	v_mov_b32_e32 v101, v30
	v_mov_b32_e32 v102, v30
	v_mov_b32_e32 v103, v30
	v_mov_b32_e32 v22, v30
	v_mov_b32_e32 v23, v30
	v_mov_b32_e32 v24, v30
	v_mov_b32_e32 v25, v30
	v_mov_b32_e32 v18, v30
	v_mov_b32_e32 v19, v30
	v_mov_b32_e32 v20, v30
	v_mov_b32_e32 v21, v30
	v_mov_b32_e32 v14, v30
	v_mov_b32_e32 v15, v30
	v_mov_b32_e32 v16, v30
	v_mov_b32_e32 v17, v30
	v_mov_b32_e32 v10, v30
	v_mov_b32_e32 v11, v30
	v_mov_b32_e32 v12, v30
	v_mov_b32_e32 v13, v30
	s_waitcnt lgkmcnt(0)
	s_barrier
.LBB0_466:
	v_add_u32_e32 v138, 0x10400, v151
	ds_read_b128 v[164:167], v151 offset:16640
	ds_read_b128 v[172:175], v151 offset:33280
	ds_read_b128 v[168:171], v151 offset:49920
	ds_read_b128 v[176:179], v138 offset:0
	s_waitcnt vmcnt(34)
	s_waitcnt lgkmcnt(3)
	v_mfma_f32_16x16x32_bf16 v[100:103], v[74:77], v[164:167], v[100:103]
	v_mfma_f32_16x16x32_bf16 v[62:65], v[96:99], v[164:167], v[62:65]
	v_mfma_f32_16x16x32_bf16 v[42:45], v[92:95], v[164:167], v[42:45]
	v_mfma_f32_16x16x32_bf16 v[22:25], v[88:91], v[164:167], v[22:25]
	ds_read_b128 v[164:167], v151 offset:16704
	s_waitcnt lgkmcnt(3)
	v_mfma_f32_16x16x32_bf16 v[80:83], v[74:77], v[172:175], v[80:83]
	v_mfma_f32_16x16x32_bf16 v[58:61], v[96:99], v[172:175], v[58:61]
	v_mfma_f32_16x16x32_bf16 v[38:41], v[92:95], v[172:175], v[38:41]
	v_mfma_f32_16x16x32_bf16 v[18:21], v[88:91], v[172:175], v[18:21]
	ds_read_b128 v[172:175], v151 offset:33344
	s_waitcnt lgkmcnt(3)
	v_mfma_f32_16x16x32_bf16 v[84:87], v[74:77], v[168:171], v[84:87]
	v_mfma_f32_16x16x32_bf16 v[54:57], v[96:99], v[168:171], v[54:57]
	v_mfma_f32_16x16x32_bf16 v[34:37], v[92:95], v[168:171], v[34:37]
	v_mfma_f32_16x16x32_bf16 v[14:17], v[88:91], v[168:171], v[14:17]
	ds_read_b128 v[168:171], v151 offset:49984
	s_waitcnt lgkmcnt(3)
	v_mfma_f32_16x16x32_bf16 v[70:73], v[74:77], v[176:179], v[70:73]
	v_mfma_f32_16x16x32_bf16 v[50:53], v[96:99], v[176:179], v[50:53]
	v_mfma_f32_16x16x32_bf16 v[30:33], v[92:95], v[176:179], v[30:33]
	v_mfma_f32_16x16x32_bf16 v[10:13], v[88:91], v[176:179], v[10:13]
	ds_read_b128 v[176:179], v138 offset:64
	global_load_dwordx4 v[74:77], v239, s[36:37] offset:320
	global_load_dwordx4 v[96:99], v239, s[38:39] offset:320
	global_load_dwordx4 v[92:95], v239, s[40:41] offset:320
	global_load_dwordx4 v[88:91], v239, s[44:45] offset:320
	s_waitcnt vmcnt(32)
	s_waitcnt lgkmcnt(3)
	v_mfma_f32_16x16x32_bf16 v[100:103], v[140:143], v[164:167], v[100:103]
	v_mfma_f32_16x16x32_bf16 v[62:65], v[152:155], v[164:167], v[62:65]
	v_mfma_f32_16x16x32_bf16 v[42:45], v[156:159], v[164:167], v[42:45]
	v_mfma_f32_16x16x32_bf16 v[22:25], v[160:163], v[164:167], v[22:25]
	ds_read_b128 v[164:167], v151 offset:16768
	s_waitcnt lgkmcnt(3)
	v_mfma_f32_16x16x32_bf16 v[80:83], v[140:143], v[172:175], v[80:83]
	v_mfma_f32_16x16x32_bf16 v[58:61], v[152:155], v[172:175], v[58:61]
	v_mfma_f32_16x16x32_bf16 v[38:41], v[156:159], v[172:175], v[38:41]
	v_mfma_f32_16x16x32_bf16 v[18:21], v[160:163], v[172:175], v[18:21]
	ds_read_b128 v[172:175], v151 offset:33408
	s_waitcnt lgkmcnt(3)
	v_mfma_f32_16x16x32_bf16 v[84:87], v[140:143], v[168:171], v[84:87]
	v_mfma_f32_16x16x32_bf16 v[54:57], v[152:155], v[168:171], v[54:57]
	v_mfma_f32_16x16x32_bf16 v[34:37], v[156:159], v[168:171], v[34:37]
	v_mfma_f32_16x16x32_bf16 v[14:17], v[160:163], v[168:171], v[14:17]
	ds_read_b128 v[168:171], v151 offset:50048
	s_waitcnt lgkmcnt(3)
	v_mfma_f32_16x16x32_bf16 v[70:73], v[140:143], v[176:179], v[70:73]
	v_mfma_f32_16x16x32_bf16 v[50:53], v[152:155], v[176:179], v[50:53]
	v_mfma_f32_16x16x32_bf16 v[30:33], v[156:159], v[176:179], v[30:33]
	v_mfma_f32_16x16x32_bf16 v[10:13], v[160:163], v[176:179], v[10:13]
	ds_read_b128 v[176:179], v138 offset:128
	global_load_dwordx4 v[140:143], v239, s[36:37] offset:384
	global_load_dwordx4 v[152:155], v239, s[38:39] offset:384
	global_load_dwordx4 v[156:159], v239, s[40:41] offset:384
	global_load_dwordx4 v[160:163], v239, s[44:45] offset:384
	s_waitcnt vmcnt(32)
	s_waitcnt lgkmcnt(3)
	v_mfma_f32_16x16x32_bf16 v[100:103], v[180:183], v[164:167], v[100:103]
	v_mfma_f32_16x16x32_bf16 v[62:65], v[184:187], v[164:167], v[62:65]
	v_mfma_f32_16x16x32_bf16 v[42:45], v[188:191], v[164:167], v[42:45]
	v_mfma_f32_16x16x32_bf16 v[22:25], v[192:195], v[164:167], v[22:25]
	ds_read_b128 v[164:167], v151 offset:16832
	s_waitcnt lgkmcnt(3)
	v_mfma_f32_16x16x32_bf16 v[80:83], v[180:183], v[172:175], v[80:83]
	v_mfma_f32_16x16x32_bf16 v[58:61], v[184:187], v[172:175], v[58:61]
	v_mfma_f32_16x16x32_bf16 v[38:41], v[188:191], v[172:175], v[38:41]
	v_mfma_f32_16x16x32_bf16 v[18:21], v[192:195], v[172:175], v[18:21]
	ds_read_b128 v[172:175], v151 offset:33472
	s_waitcnt lgkmcnt(3)
	v_mfma_f32_16x16x32_bf16 v[84:87], v[180:183], v[168:171], v[84:87]
	v_mfma_f32_16x16x32_bf16 v[54:57], v[184:187], v[168:171], v[54:57]
	v_mfma_f32_16x16x32_bf16 v[34:37], v[188:191], v[168:171], v[34:37]
	v_mfma_f32_16x16x32_bf16 v[14:17], v[192:195], v[168:171], v[14:17]
	ds_read_b128 v[168:171], v151 offset:50112
	s_waitcnt lgkmcnt(3)
	v_mfma_f32_16x16x32_bf16 v[70:73], v[180:183], v[176:179], v[70:73]
	v_mfma_f32_16x16x32_bf16 v[50:53], v[184:187], v[176:179], v[50:53]
	v_mfma_f32_16x16x32_bf16 v[30:33], v[188:191], v[176:179], v[30:33]
	v_mfma_f32_16x16x32_bf16 v[10:13], v[192:195], v[176:179], v[10:13]
	ds_read_b128 v[176:179], v138 offset:192
	global_load_dwordx4 v[180:183], v239, s[36:37] offset:448
	global_load_dwordx4 v[184:187], v239, s[38:39] offset:448
	global_load_dwordx4 v[188:191], v239, s[40:41] offset:448
	global_load_dwordx4 v[192:195], v239, s[44:45] offset:448
	s_waitcnt vmcnt(32)
	s_waitcnt lgkmcnt(3)
	v_mfma_f32_16x16x32_bf16 v[100:103], v[196:199], v[164:167], v[100:103]
	v_mfma_f32_16x16x32_bf16 v[62:65], v[200:203], v[164:167], v[62:65]
	v_mfma_f32_16x16x32_bf16 v[42:45], v[204:207], v[164:167], v[42:45]
	v_mfma_f32_16x16x32_bf16 v[22:25], v[208:211], v[164:167], v[22:25]
	ds_read_b128 v[164:167], v151 offset:16896
	s_waitcnt lgkmcnt(3)
	v_mfma_f32_16x16x32_bf16 v[80:83], v[196:199], v[172:175], v[80:83]
	v_mfma_f32_16x16x32_bf16 v[58:61], v[200:203], v[172:175], v[58:61]
	v_mfma_f32_16x16x32_bf16 v[38:41], v[204:207], v[172:175], v[38:41]
	v_mfma_f32_16x16x32_bf16 v[18:21], v[208:211], v[172:175], v[18:21]
	ds_read_b128 v[172:175], v151 offset:33536
	s_waitcnt lgkmcnt(3)
	v_mfma_f32_16x16x32_bf16 v[84:87], v[196:199], v[168:171], v[84:87]
	v_mfma_f32_16x16x32_bf16 v[54:57], v[200:203], v[168:171], v[54:57]
	v_mfma_f32_16x16x32_bf16 v[34:37], v[204:207], v[168:171], v[34:37]
	v_mfma_f32_16x16x32_bf16 v[14:17], v[208:211], v[168:171], v[14:17]
	ds_read_b128 v[168:171], v151 offset:50176
	s_waitcnt lgkmcnt(3)
	v_mfma_f32_16x16x32_bf16 v[70:73], v[196:199], v[176:179], v[70:73]
	v_mfma_f32_16x16x32_bf16 v[50:53], v[200:203], v[176:179], v[50:53]
	v_mfma_f32_16x16x32_bf16 v[30:33], v[204:207], v[176:179], v[30:33]
	v_mfma_f32_16x16x32_bf16 v[10:13], v[208:211], v[176:179], v[10:13]
	ds_read_b128 v[176:179], v138 offset:256
	global_load_dwordx4 v[196:199], v239, s[36:37] offset:512
	global_load_dwordx4 v[200:203], v239, s[38:39] offset:512
	global_load_dwordx4 v[204:207], v239, s[40:41] offset:512
	global_load_dwordx4 v[208:211], v239, s[44:45] offset:512
	s_waitcnt vmcnt(32)
	s_waitcnt lgkmcnt(3)
	v_mfma_f32_16x16x32_bf16 v[100:103], v[212:215], v[164:167], v[100:103]
	v_mfma_f32_16x16x32_bf16 v[62:65], v[216:219], v[164:167], v[62:65]
	v_mfma_f32_16x16x32_bf16 v[42:45], v[240:243], v[164:167], v[42:45]
	v_mfma_f32_16x16x32_bf16 v[22:25], v[244:247], v[164:167], v[22:25]
	ds_read_b128 v[164:167], v151 offset:16960
	s_waitcnt lgkmcnt(3)
	v_mfma_f32_16x16x32_bf16 v[80:83], v[212:215], v[172:175], v[80:83]
	v_mfma_f32_16x16x32_bf16 v[58:61], v[216:219], v[172:175], v[58:61]
	v_mfma_f32_16x16x32_bf16 v[38:41], v[240:243], v[172:175], v[38:41]
	v_mfma_f32_16x16x32_bf16 v[18:21], v[244:247], v[172:175], v[18:21]
	ds_read_b128 v[172:175], v151 offset:33600
	s_waitcnt lgkmcnt(3)
	v_mfma_f32_16x16x32_bf16 v[84:87], v[212:215], v[168:171], v[84:87]
	v_mfma_f32_16x16x32_bf16 v[54:57], v[216:219], v[168:171], v[54:57]
	v_mfma_f32_16x16x32_bf16 v[34:37], v[240:243], v[168:171], v[34:37]
	v_mfma_f32_16x16x32_bf16 v[14:17], v[244:247], v[168:171], v[14:17]
	ds_read_b128 v[168:171], v151 offset:50240
	s_waitcnt lgkmcnt(3)
	v_mfma_f32_16x16x32_bf16 v[70:73], v[212:215], v[176:179], v[70:73]
	v_mfma_f32_16x16x32_bf16 v[50:53], v[216:219], v[176:179], v[50:53]
	v_mfma_f32_16x16x32_bf16 v[30:33], v[240:243], v[176:179], v[30:33]
	v_mfma_f32_16x16x32_bf16 v[10:13], v[244:247], v[176:179], v[10:13]
	ds_read_b128 v[176:179], v138 offset:320
	global_load_dwordx4 v[212:215], v239, s[36:37] offset:576
	global_load_dwordx4 v[216:219], v239, s[38:39] offset:576
	global_load_dwordx4 v[240:243], v239, s[40:41] offset:576
	global_load_dwordx4 v[244:247], v239, s[44:45] offset:576
	s_waitcnt vmcnt(16)
	s_waitcnt lgkmcnt(3)
	v_mfma_f32_16x16x32_bf16 v[100:103], v[74:77], v[164:167], v[100:103]
	v_mfma_f32_16x16x32_bf16 v[62:65], v[96:99], v[164:167], v[62:65]
	v_mfma_f32_16x16x32_bf16 v[42:45], v[92:95], v[164:167], v[42:45]
	v_mfma_f32_16x16x32_bf16 v[22:25], v[88:91], v[164:167], v[22:25]
	ds_read_b128 v[164:167], v151 offset:17024
	s_waitcnt lgkmcnt(3)
	v_mfma_f32_16x16x32_bf16 v[80:83], v[74:77], v[172:175], v[80:83]
	v_mfma_f32_16x16x32_bf16 v[58:61], v[96:99], v[172:175], v[58:61]
	v_mfma_f32_16x16x32_bf16 v[38:41], v[92:95], v[172:175], v[38:41]
	v_mfma_f32_16x16x32_bf16 v[18:21], v[88:91], v[172:175], v[18:21]
	ds_read_b128 v[172:175], v151 offset:33664
	s_waitcnt lgkmcnt(3)
	v_mfma_f32_16x16x32_bf16 v[84:87], v[74:77], v[168:171], v[84:87]
	v_mfma_f32_16x16x32_bf16 v[54:57], v[96:99], v[168:171], v[54:57]
	v_mfma_f32_16x16x32_bf16 v[34:37], v[92:95], v[168:171], v[34:37]
	v_mfma_f32_16x16x32_bf16 v[14:17], v[88:91], v[168:171], v[14:17]
	ds_read_b128 v[168:171], v151 offset:50304
	s_waitcnt lgkmcnt(3)
	v_mfma_f32_16x16x32_bf16 v[70:73], v[74:77], v[176:179], v[70:73]
	v_mfma_f32_16x16x32_bf16 v[50:53], v[96:99], v[176:179], v[50:53]
	v_mfma_f32_16x16x32_bf16 v[30:33], v[92:95], v[176:179], v[30:33]
	v_mfma_f32_16x16x32_bf16 v[10:13], v[88:91], v[176:179], v[10:13]
	ds_read_b128 v[176:179], v138 offset:384
	global_load_dwordx4 v[74:77], v239, s[36:37] offset:640
	global_load_dwordx4 v[96:99], v239, s[38:39] offset:640
	global_load_dwordx4 v[92:95], v239, s[40:41] offset:640
	global_load_dwordx4 v[88:91], v239, s[44:45] offset:640
	s_waitcnt vmcnt(16)
	s_waitcnt lgkmcnt(3)
	v_mfma_f32_16x16x32_bf16 v[100:103], v[140:143], v[164:167], v[100:103]
	v_mfma_f32_16x16x32_bf16 v[62:65], v[152:155], v[164:167], v[62:65]
	v_mfma_f32_16x16x32_bf16 v[42:45], v[156:159], v[164:167], v[42:45]
	v_mfma_f32_16x16x32_bf16 v[22:25], v[160:163], v[164:167], v[22:25]
	ds_read_b128 v[164:167], v151 offset:17088
	s_waitcnt lgkmcnt(3)
	v_mfma_f32_16x16x32_bf16 v[80:83], v[140:143], v[172:175], v[80:83]
	v_mfma_f32_16x16x32_bf16 v[58:61], v[152:155], v[172:175], v[58:61]
	v_mfma_f32_16x16x32_bf16 v[38:41], v[156:159], v[172:175], v[38:41]
	v_mfma_f32_16x16x32_bf16 v[18:21], v[160:163], v[172:175], v[18:21]
	ds_read_b128 v[172:175], v151 offset:33728
	s_waitcnt lgkmcnt(3)
	v_mfma_f32_16x16x32_bf16 v[84:87], v[140:143], v[168:171], v[84:87]
	v_mfma_f32_16x16x32_bf16 v[54:57], v[152:155], v[168:171], v[54:57]
	v_mfma_f32_16x16x32_bf16 v[34:37], v[156:159], v[168:171], v[34:37]
	v_mfma_f32_16x16x32_bf16 v[14:17], v[160:163], v[168:171], v[14:17]
	ds_read_b128 v[168:171], v151 offset:50368
	s_waitcnt lgkmcnt(3)
	v_mfma_f32_16x16x32_bf16 v[70:73], v[140:143], v[176:179], v[70:73]
	v_mfma_f32_16x16x32_bf16 v[50:53], v[152:155], v[176:179], v[50:53]
	v_mfma_f32_16x16x32_bf16 v[30:33], v[156:159], v[176:179], v[30:33]
	v_mfma_f32_16x16x32_bf16 v[10:13], v[160:163], v[176:179], v[10:13]
	ds_read_b128 v[176:179], v138 offset:448
	global_load_dwordx4 v[140:143], v239, s[36:37] offset:704
	global_load_dwordx4 v[152:155], v239, s[38:39] offset:704
	global_load_dwordx4 v[156:159], v239, s[40:41] offset:704
	global_load_dwordx4 v[160:163], v239, s[44:45] offset:704
	s_waitcnt vmcnt(16)
	s_waitcnt lgkmcnt(3)
	v_mfma_f32_16x16x32_bf16 v[100:103], v[180:183], v[164:167], v[100:103]
	v_mfma_f32_16x16x32_bf16 v[62:65], v[184:187], v[164:167], v[62:65]
	v_mfma_f32_16x16x32_bf16 v[42:45], v[188:191], v[164:167], v[42:45]
	v_mfma_f32_16x16x32_bf16 v[22:25], v[192:195], v[164:167], v[22:25]
	ds_read_b128 v[164:167], v151 offset:17152
	s_waitcnt lgkmcnt(3)
	v_mfma_f32_16x16x32_bf16 v[80:83], v[180:183], v[172:175], v[80:83]
	v_mfma_f32_16x16x32_bf16 v[58:61], v[184:187], v[172:175], v[58:61]
	v_mfma_f32_16x16x32_bf16 v[38:41], v[188:191], v[172:175], v[38:41]
	v_mfma_f32_16x16x32_bf16 v[18:21], v[192:195], v[172:175], v[18:21]
	ds_read_b128 v[172:175], v151 offset:33792
	s_waitcnt lgkmcnt(3)
	v_mfma_f32_16x16x32_bf16 v[84:87], v[180:183], v[168:171], v[84:87]
	v_mfma_f32_16x16x32_bf16 v[54:57], v[184:187], v[168:171], v[54:57]
	v_mfma_f32_16x16x32_bf16 v[34:37], v[188:191], v[168:171], v[34:37]
	v_mfma_f32_16x16x32_bf16 v[14:17], v[192:195], v[168:171], v[14:17]
	ds_read_b128 v[168:171], v151 offset:50432
	s_waitcnt lgkmcnt(3)
	v_mfma_f32_16x16x32_bf16 v[70:73], v[180:183], v[176:179], v[70:73]
	v_mfma_f32_16x16x32_bf16 v[50:53], v[184:187], v[176:179], v[50:53]
	v_mfma_f32_16x16x32_bf16 v[30:33], v[188:191], v[176:179], v[30:33]
	v_mfma_f32_16x16x32_bf16 v[10:13], v[192:195], v[176:179], v[10:13]
	ds_read_b128 v[176:179], v138 offset:512
	global_load_dwordx4 v[180:183], v239, s[36:37] offset:768
	global_load_dwordx4 v[184:187], v239, s[38:39] offset:768
	global_load_dwordx4 v[188:191], v239, s[40:41] offset:768
	global_load_dwordx4 v[192:195], v239, s[44:45] offset:768
	s_waitcnt vmcnt(16)
	s_waitcnt lgkmcnt(3)
	v_mfma_f32_16x16x32_bf16 v[100:103], v[196:199], v[164:167], v[100:103]
	v_mfma_f32_16x16x32_bf16 v[62:65], v[200:203], v[164:167], v[62:65]
	v_mfma_f32_16x16x32_bf16 v[42:45], v[204:207], v[164:167], v[42:45]
	v_mfma_f32_16x16x32_bf16 v[22:25], v[208:211], v[164:167], v[22:25]
	ds_read_b128 v[164:167], v151 offset:17216
	s_waitcnt lgkmcnt(3)
	v_mfma_f32_16x16x32_bf16 v[80:83], v[196:199], v[172:175], v[80:83]
	v_mfma_f32_16x16x32_bf16 v[58:61], v[200:203], v[172:175], v[58:61]
	v_mfma_f32_16x16x32_bf16 v[38:41], v[204:207], v[172:175], v[38:41]
	v_mfma_f32_16x16x32_bf16 v[18:21], v[208:211], v[172:175], v[18:21]
	ds_read_b128 v[172:175], v151 offset:33856
	s_waitcnt lgkmcnt(3)
	v_mfma_f32_16x16x32_bf16 v[84:87], v[196:199], v[168:171], v[84:87]
	v_mfma_f32_16x16x32_bf16 v[54:57], v[200:203], v[168:171], v[54:57]
	v_mfma_f32_16x16x32_bf16 v[34:37], v[204:207], v[168:171], v[34:37]
	v_mfma_f32_16x16x32_bf16 v[14:17], v[208:211], v[168:171], v[14:17]
	ds_read_b128 v[168:171], v151 offset:50496
	s_waitcnt lgkmcnt(3)
	v_mfma_f32_16x16x32_bf16 v[70:73], v[196:199], v[176:179], v[70:73]
	v_mfma_f32_16x16x32_bf16 v[50:53], v[200:203], v[176:179], v[50:53]
	v_mfma_f32_16x16x32_bf16 v[30:33], v[204:207], v[176:179], v[30:33]
	v_mfma_f32_16x16x32_bf16 v[10:13], v[208:211], v[176:179], v[10:13]
	ds_read_b128 v[176:179], v138 offset:576
	global_load_dwordx4 v[196:199], v239, s[36:37] offset:832
	global_load_dwordx4 v[200:203], v239, s[38:39] offset:832
	global_load_dwordx4 v[204:207], v239, s[40:41] offset:832
	global_load_dwordx4 v[208:211], v239, s[44:45] offset:832
	s_waitcnt vmcnt(16)
	s_waitcnt lgkmcnt(3)
	v_mfma_f32_16x16x32_bf16 v[100:103], v[212:215], v[164:167], v[100:103]
	v_mfma_f32_16x16x32_bf16 v[62:65], v[216:219], v[164:167], v[62:65]
	v_mfma_f32_16x16x32_bf16 v[42:45], v[240:243], v[164:167], v[42:45]
	v_mfma_f32_16x16x32_bf16 v[22:25], v[244:247], v[164:167], v[22:25]
	ds_read_b128 v[164:167], v151 offset:17280
	s_waitcnt lgkmcnt(3)
	v_mfma_f32_16x16x32_bf16 v[80:83], v[212:215], v[172:175], v[80:83]
	v_mfma_f32_16x16x32_bf16 v[58:61], v[216:219], v[172:175], v[58:61]
	v_mfma_f32_16x16x32_bf16 v[38:41], v[240:243], v[172:175], v[38:41]
	v_mfma_f32_16x16x32_bf16 v[18:21], v[244:247], v[172:175], v[18:21]
	ds_read_b128 v[172:175], v151 offset:33920
	s_waitcnt lgkmcnt(3)
	v_mfma_f32_16x16x32_bf16 v[84:87], v[212:215], v[168:171], v[84:87]
	v_mfma_f32_16x16x32_bf16 v[54:57], v[216:219], v[168:171], v[54:57]
	v_mfma_f32_16x16x32_bf16 v[34:37], v[240:243], v[168:171], v[34:37]
	v_mfma_f32_16x16x32_bf16 v[14:17], v[244:247], v[168:171], v[14:17]
	ds_read_b128 v[168:171], v151 offset:50560
	s_waitcnt lgkmcnt(3)
	v_mfma_f32_16x16x32_bf16 v[70:73], v[212:215], v[176:179], v[70:73]
	v_mfma_f32_16x16x32_bf16 v[50:53], v[216:219], v[176:179], v[50:53]
	v_mfma_f32_16x16x32_bf16 v[30:33], v[240:243], v[176:179], v[30:33]
	v_mfma_f32_16x16x32_bf16 v[10:13], v[244:247], v[176:179], v[10:13]
	ds_read_b128 v[176:179], v138 offset:640
	global_load_dwordx4 v[212:215], v239, s[36:37] offset:896
	global_load_dwordx4 v[216:219], v239, s[38:39] offset:896
	global_load_dwordx4 v[240:243], v239, s[40:41] offset:896
	global_load_dwordx4 v[244:247], v239, s[44:45] offset:896
	s_waitcnt vmcnt(16)
	s_waitcnt lgkmcnt(3)
	v_mfma_f32_16x16x32_bf16 v[100:103], v[74:77], v[164:167], v[100:103]
	v_mfma_f32_16x16x32_bf16 v[62:65], v[96:99], v[164:167], v[62:65]
	v_mfma_f32_16x16x32_bf16 v[42:45], v[92:95], v[164:167], v[42:45]
	v_mfma_f32_16x16x32_bf16 v[22:25], v[88:91], v[164:167], v[22:25]
	ds_read_b128 v[164:167], v151 offset:17344
	s_waitcnt lgkmcnt(3)
	v_mfma_f32_16x16x32_bf16 v[80:83], v[74:77], v[172:175], v[80:83]
	v_mfma_f32_16x16x32_bf16 v[58:61], v[96:99], v[172:175], v[58:61]
	v_mfma_f32_16x16x32_bf16 v[38:41], v[92:95], v[172:175], v[38:41]
	v_mfma_f32_16x16x32_bf16 v[18:21], v[88:91], v[172:175], v[18:21]
	ds_read_b128 v[172:175], v151 offset:33984
	s_waitcnt lgkmcnt(3)
	v_mfma_f32_16x16x32_bf16 v[84:87], v[74:77], v[168:171], v[84:87]
	v_mfma_f32_16x16x32_bf16 v[54:57], v[96:99], v[168:171], v[54:57]
	v_mfma_f32_16x16x32_bf16 v[34:37], v[92:95], v[168:171], v[34:37]
	v_mfma_f32_16x16x32_bf16 v[14:17], v[88:91], v[168:171], v[14:17]
	ds_read_b128 v[168:171], v151 offset:50624
	s_waitcnt lgkmcnt(3)
	v_mfma_f32_16x16x32_bf16 v[70:73], v[74:77], v[176:179], v[70:73]
	v_mfma_f32_16x16x32_bf16 v[50:53], v[96:99], v[176:179], v[50:53]
	v_mfma_f32_16x16x32_bf16 v[30:33], v[92:95], v[176:179], v[30:33]
	v_mfma_f32_16x16x32_bf16 v[10:13], v[88:91], v[176:179], v[10:13]
	ds_read_b128 v[176:179], v138 offset:704
	global_load_dwordx4 v[74:77], v239, s[36:37] offset:960
	global_load_dwordx4 v[96:99], v239, s[38:39] offset:960
	global_load_dwordx4 v[92:95], v239, s[40:41] offset:960
	global_load_dwordx4 v[88:91], v239, s[44:45] offset:960
	s_waitcnt vmcnt(16)
	s_waitcnt lgkmcnt(3)
	v_mfma_f32_16x16x32_bf16 v[100:103], v[140:143], v[164:167], v[100:103]
	v_mfma_f32_16x16x32_bf16 v[62:65], v[152:155], v[164:167], v[62:65]
	v_mfma_f32_16x16x32_bf16 v[42:45], v[156:159], v[164:167], v[42:45]
	v_mfma_f32_16x16x32_bf16 v[22:25], v[160:163], v[164:167], v[22:25]
	ds_read_b128 v[164:167], v151 offset:17408
	s_waitcnt lgkmcnt(3)
	v_mfma_f32_16x16x32_bf16 v[80:83], v[140:143], v[172:175], v[80:83]
	v_mfma_f32_16x16x32_bf16 v[58:61], v[152:155], v[172:175], v[58:61]
	v_mfma_f32_16x16x32_bf16 v[38:41], v[156:159], v[172:175], v[38:41]
	v_mfma_f32_16x16x32_bf16 v[18:21], v[160:163], v[172:175], v[18:21]
	ds_read_b128 v[172:175], v151 offset:34048
	s_waitcnt lgkmcnt(3)
	v_mfma_f32_16x16x32_bf16 v[84:87], v[140:143], v[168:171], v[84:87]
	v_mfma_f32_16x16x32_bf16 v[54:57], v[152:155], v[168:171], v[54:57]
	v_mfma_f32_16x16x32_bf16 v[34:37], v[156:159], v[168:171], v[34:37]
	v_mfma_f32_16x16x32_bf16 v[14:17], v[160:163], v[168:171], v[14:17]
	ds_read_b128 v[168:171], v151 offset:50688
	s_waitcnt lgkmcnt(3)
	v_mfma_f32_16x16x32_bf16 v[70:73], v[140:143], v[176:179], v[70:73]
	v_mfma_f32_16x16x32_bf16 v[50:53], v[152:155], v[176:179], v[50:53]
	v_mfma_f32_16x16x32_bf16 v[30:33], v[156:159], v[176:179], v[30:33]
	v_mfma_f32_16x16x32_bf16 v[10:13], v[160:163], v[176:179], v[10:13]
	ds_read_b128 v[176:179], v138 offset:768
	s_waitcnt vmcnt(12)
	s_waitcnt lgkmcnt(3)
	v_mfma_f32_16x16x32_bf16 v[100:103], v[180:183], v[164:167], v[100:103]
	v_mfma_f32_16x16x32_bf16 v[62:65], v[184:187], v[164:167], v[62:65]
	v_mfma_f32_16x16x32_bf16 v[42:45], v[188:191], v[164:167], v[42:45]
	v_mfma_f32_16x16x32_bf16 v[22:25], v[192:195], v[164:167], v[22:25]
	ds_read_b128 v[164:167], v151 offset:17472
	s_waitcnt lgkmcnt(3)
	v_mfma_f32_16x16x32_bf16 v[80:83], v[180:183], v[172:175], v[80:83]
	v_mfma_f32_16x16x32_bf16 v[58:61], v[184:187], v[172:175], v[58:61]
	v_mfma_f32_16x16x32_bf16 v[38:41], v[188:191], v[172:175], v[38:41]
	v_mfma_f32_16x16x32_bf16 v[18:21], v[192:195], v[172:175], v[18:21]
	ds_read_b128 v[172:175], v151 offset:34112
	s_waitcnt lgkmcnt(3)
	v_mfma_f32_16x16x32_bf16 v[84:87], v[180:183], v[168:171], v[84:87]
	v_mfma_f32_16x16x32_bf16 v[54:57], v[184:187], v[168:171], v[54:57]
	v_mfma_f32_16x16x32_bf16 v[34:37], v[188:191], v[168:171], v[34:37]
	v_mfma_f32_16x16x32_bf16 v[14:17], v[192:195], v[168:171], v[14:17]
	ds_read_b128 v[168:171], v151 offset:50752
	s_waitcnt lgkmcnt(3)
	v_mfma_f32_16x16x32_bf16 v[70:73], v[180:183], v[176:179], v[70:73]
	v_mfma_f32_16x16x32_bf16 v[50:53], v[184:187], v[176:179], v[50:53]
	v_mfma_f32_16x16x32_bf16 v[30:33], v[188:191], v[176:179], v[30:33]
	v_mfma_f32_16x16x32_bf16 v[10:13], v[192:195], v[176:179], v[10:13]
	ds_read_b128 v[176:179], v138 offset:832
	s_waitcnt vmcnt(8)
	s_waitcnt lgkmcnt(3)
	v_mfma_f32_16x16x32_bf16 v[100:103], v[196:199], v[164:167], v[100:103]
	v_mfma_f32_16x16x32_bf16 v[62:65], v[200:203], v[164:167], v[62:65]
	v_mfma_f32_16x16x32_bf16 v[42:45], v[204:207], v[164:167], v[42:45]
	v_mfma_f32_16x16x32_bf16 v[22:25], v[208:211], v[164:167], v[22:25]
	ds_read_b128 v[164:167], v151 offset:17536
	s_waitcnt lgkmcnt(3)
	v_mfma_f32_16x16x32_bf16 v[80:83], v[196:199], v[172:175], v[80:83]
	v_mfma_f32_16x16x32_bf16 v[58:61], v[200:203], v[172:175], v[58:61]
	v_mfma_f32_16x16x32_bf16 v[38:41], v[204:207], v[172:175], v[38:41]
	v_mfma_f32_16x16x32_bf16 v[18:21], v[208:211], v[172:175], v[18:21]
	ds_read_b128 v[172:175], v151 offset:34176
	s_waitcnt lgkmcnt(3)
	v_mfma_f32_16x16x32_bf16 v[84:87], v[196:199], v[168:171], v[84:87]
	v_mfma_f32_16x16x32_bf16 v[54:57], v[200:203], v[168:171], v[54:57]
	v_mfma_f32_16x16x32_bf16 v[34:37], v[204:207], v[168:171], v[34:37]
	v_mfma_f32_16x16x32_bf16 v[14:17], v[208:211], v[168:171], v[14:17]
	ds_read_b128 v[168:171], v151 offset:50816
	s_waitcnt lgkmcnt(3)
	v_mfma_f32_16x16x32_bf16 v[70:73], v[196:199], v[176:179], v[70:73]
	v_mfma_f32_16x16x32_bf16 v[50:53], v[200:203], v[176:179], v[50:53]
	v_mfma_f32_16x16x32_bf16 v[30:33], v[204:207], v[176:179], v[30:33]
	v_mfma_f32_16x16x32_bf16 v[10:13], v[208:211], v[176:179], v[10:13]
	ds_read_b128 v[176:179], v138 offset:896
	s_waitcnt vmcnt(4)
	s_waitcnt lgkmcnt(3)
	v_mfma_f32_16x16x32_bf16 v[100:103], v[212:215], v[164:167], v[100:103]
	v_mfma_f32_16x16x32_bf16 v[62:65], v[216:219], v[164:167], v[62:65]
	v_mfma_f32_16x16x32_bf16 v[42:45], v[240:243], v[164:167], v[42:45]
	v_mfma_f32_16x16x32_bf16 v[22:25], v[244:247], v[164:167], v[22:25]
	ds_read_b128 v[164:167], v151 offset:17600
	s_waitcnt lgkmcnt(3)
	v_mfma_f32_16x16x32_bf16 v[80:83], v[212:215], v[172:175], v[80:83]
	v_mfma_f32_16x16x32_bf16 v[58:61], v[216:219], v[172:175], v[58:61]
	v_mfma_f32_16x16x32_bf16 v[38:41], v[240:243], v[172:175], v[38:41]
	v_mfma_f32_16x16x32_bf16 v[18:21], v[244:247], v[172:175], v[18:21]
	ds_read_b128 v[172:175], v151 offset:34240
	s_waitcnt lgkmcnt(3)
	v_mfma_f32_16x16x32_bf16 v[84:87], v[212:215], v[168:171], v[84:87]
	v_mfma_f32_16x16x32_bf16 v[54:57], v[216:219], v[168:171], v[54:57]
	v_mfma_f32_16x16x32_bf16 v[34:37], v[240:243], v[168:171], v[34:37]
	v_mfma_f32_16x16x32_bf16 v[14:17], v[244:247], v[168:171], v[14:17]
	ds_read_b128 v[168:171], v151 offset:50880
	s_waitcnt lgkmcnt(3)
	v_mfma_f32_16x16x32_bf16 v[70:73], v[212:215], v[176:179], v[70:73]
	v_mfma_f32_16x16x32_bf16 v[50:53], v[216:219], v[176:179], v[50:53]
	v_mfma_f32_16x16x32_bf16 v[30:33], v[240:243], v[176:179], v[30:33]
	v_mfma_f32_16x16x32_bf16 v[10:13], v[244:247], v[176:179], v[10:13]
	ds_read_b128 v[176:179], v138 offset:960
	s_waitcnt vmcnt(0)
	s_waitcnt lgkmcnt(3)
	v_mfma_f32_16x16x32_bf16 v[100:103], v[74:77], v[164:167], v[100:103]
	v_mfma_f32_16x16x32_bf16 v[62:65], v[96:99], v[164:167], v[62:65]
	v_mfma_f32_16x16x32_bf16 v[42:45], v[92:95], v[164:167], v[42:45]
	v_mfma_f32_16x16x32_bf16 v[22:25], v[88:91], v[164:167], v[22:25]
	s_waitcnt lgkmcnt(2)
	v_mfma_f32_16x16x32_bf16 v[80:83], v[74:77], v[172:175], v[80:83]
	v_mfma_f32_16x16x32_bf16 v[58:61], v[96:99], v[172:175], v[58:61]
	v_mfma_f32_16x16x32_bf16 v[38:41], v[92:95], v[172:175], v[38:41]
	v_mfma_f32_16x16x32_bf16 v[18:21], v[88:91], v[172:175], v[18:21]
	s_waitcnt lgkmcnt(1)
	v_mfma_f32_16x16x32_bf16 v[84:87], v[74:77], v[168:171], v[84:87]
	v_mfma_f32_16x16x32_bf16 v[54:57], v[96:99], v[168:171], v[54:57]
	v_mfma_f32_16x16x32_bf16 v[34:37], v[92:95], v[168:171], v[34:37]
	v_mfma_f32_16x16x32_bf16 v[14:17], v[88:91], v[168:171], v[14:17]
	s_waitcnt lgkmcnt(0)
	v_mfma_f32_16x16x32_bf16 v[70:73], v[74:77], v[176:179], v[70:73]
	v_mfma_f32_16x16x32_bf16 v[50:53], v[96:99], v[176:179], v[50:53]
	v_mfma_f32_16x16x32_bf16 v[30:33], v[92:95], v[176:179], v[30:33]
	v_mfma_f32_16x16x32_bf16 v[10:13], v[88:91], v[176:179], v[10:13]
	s_waitcnt vmcnt(3)
	v_add_f32_e32 v76, v66, v100
	v_mul_f32_e32 v76, 0xbfb8aa3b, v76
	v_exp_f32_e32 v76, v76
	s_waitcnt vmcnt(1)
	v_lshlrev_b32_e32 v94, 16, v78
	s_waitcnt vmcnt(0)
	v_or_b32_e32 v88, s0, v146
	v_lshlrev_b32_e32 v74, 1, v88
	v_add_f32_e32 v76, 1.0, v76
	v_rcp_f32_e32 v90, v76
	v_add_f32_e32 v76, v67, v101
	v_mul_f32_e32 v76, 0xbfb8aa3b, v76
	v_exp_f32_e32 v76, v76
	v_add_u32_e32 v75, v150, v74
	v_lshlrev_b32_e32 v95, 16, v79
	v_add_u32_e32 v97, 0x4000, v75
	v_add_f32_e32 v76, 1.0, v76
	v_rcp_f32_e32 v92, v76
	v_add_f32_e32 v76, v68, v102
	v_mul_f32_e32 v76, 0xbfb8aa3b, v76
	v_exp_f32_e32 v76, v76
	v_mul_f32_e32 v75, 0xbfb8aa3b, v95
	v_exp_f32_e32 v75, v75
	v_and_b32_e32 v100, 0xffff0000, v78
	v_add_f32_e32 v76, 1.0, v76
	v_rcp_f32_e32 v91, v76
	v_add_f32_e32 v76, v69, v103
	v_mul_f32_e32 v76, 0xbfb8aa3b, v76
	v_exp_f32_e32 v76, v76
	v_and_b32_e32 v101, 0xffff0000, v79
	v_add_f32_e32 v75, 1.0, v75
	v_rcp_f32_e32 v99, v75
	v_add_f32_e32 v76, 1.0, v76
	v_rcp_f32_e32 v93, v76
	v_mul_f32_e32 v76, 0xbfb8aa3b, v94
	v_exp_f32_e32 v76, v76
	v_mul_f32_e32 v75, 0xbfb8aa3b, v101
	v_exp_f32_e32 v75, v75
	v_ashrrev_i32_e32 v89, 31, v88
	v_add_f32_e32 v76, 1.0, v76
	v_rcp_f32_e32 v98, v76
	v_mul_f32_e32 v76, 0xbfb8aa3b, v100
	v_exp_f32_e32 v76, v76
	v_add_f32_e32 v75, 1.0, v75
	v_rcp_f32_e32 v103, v75
	v_pk_mul_f32 v[94:95], v[98:99], v[94:95]
	v_add_f32_e32 v76, 1.0, v76
	v_rcp_f32_e32 v102, v76
	ds_read2_b64 v[76:79], v97 offset0:32 offset1:36
	v_lshlrev_b32_e32 v98, 16, v132
	v_lshlrev_b32_e32 v99, 16, v133
	v_readlane_b32 s0, v251, 55
	v_readlane_b32 s1, v251, 56
	s_waitcnt lgkmcnt(0)
	v_lshlrev_b32_e32 v137, 16, v77
	v_lshlrev_b32_e32 v136, 16, v76
	v_pk_mul_f32 v[90:91], v[90:91], v[136:137]
	v_and_b32_e32 v77, 0xffff0000, v77
	v_and_b32_e32 v76, 0xffff0000, v76
	v_pk_mul_f32 v[90:91], v[94:95], v[90:91]
	v_pk_mul_f32 v[76:77], v[92:93], v[76:77]
	v_pk_mul_f32 v[92:93], v[102:103], v[100:101]
	s_nop 0
	v_pk_mul_f32 v[76:77], v[92:93], v[76:77]
	s_nop 0
	v_cvt_pk_bf16_f32 v77, v91, v77
	v_cvt_pk_bf16_f32 v76, v90, v76
	v_lshlrev_b64 v[90:91], 1, v[88:89]
	v_lshl_add_u64 v[88:89], v[134:135], 0, v[90:91]
	global_store_dwordx2 v[88:89], v[76:77], off offset:2560
	v_add_f32_e32 v76, v66, v80
	v_add_f32_e32 v80, v69, v83
	v_mul_f32_e32 v80, 0xbfb8aa3b, v80
	v_exp_f32_e32 v80, v80
	v_add_f32_e32 v77, v67, v81
	v_mul_f32_e32 v77, 0xbfb8aa3b, v77
	v_add3_u32 v75, 0, v236, v74
	v_add_f32_e32 v80, 1.0, v80
	v_rcp_f32_e32 v93, v80
	v_mul_f32_e32 v80, 0xbfb8aa3b, v98
	v_exp_f32_e32 v80, v80
	v_exp_f32_e32 v77, v77
	v_add_u32_e32 v94, 0x4000, v75
	v_mul_f32_e32 v75, 0xbfb8aa3b, v99
	v_exp_f32_e32 v75, v75
	v_add_f32_e32 v80, 1.0, v80
	v_and_b32_e32 v102, 0xffff0000, v132
	v_add_f32_e32 v77, 1.0, v77
	v_rcp_f32_e32 v100, v80
	v_mul_f32_e32 v80, 0xbfb8aa3b, v102
	v_rcp_f32_e32 v92, v77
	v_add_f32_e32 v77, v68, v82
	v_exp_f32_e32 v80, v80
	v_mul_f32_e32 v76, 0xbfb8aa3b, v76
	v_mul_f32_e32 v77, 0xbfb8aa3b, v77
	v_and_b32_e32 v103, 0xffff0000, v133
	v_add_f32_e32 v75, 1.0, v75
	v_exp_f32_e32 v76, v76
	v_exp_f32_e32 v77, v77
	v_rcp_f32_e32 v101, v75
	v_mul_f32_e32 v75, 0xbfb8aa3b, v103
	v_exp_f32_e32 v75, v75
	v_add_f32_e32 v80, 1.0, v80
	v_rcp_f32_e32 v132, v80
	ds_read2_b64 v[80:83], v94 offset0:32 offset1:36
	v_add_f32_e32 v76, 1.0, v76
	v_add_f32_e32 v77, 1.0, v77
	v_rcp_f32_e32 v76, v76
	v_rcp_f32_e32 v77, v77
	v_add_f32_e32 v75, 1.0, v75
	v_rcp_f32_e32 v133, v75
	s_waitcnt lgkmcnt(0)
	v_lshlrev_b32_e32 v135, 16, v81
	v_lshlrev_b32_e32 v134, 16, v80
	v_pk_mul_f32 v[76:77], v[76:77], v[134:135]
	v_pk_mul_f32 v[98:99], v[100:101], v[98:99]
	v_and_b32_e32 v81, 0xffff0000, v81
	v_and_b32_e32 v80, 0xffff0000, v80
	v_pk_mul_f32 v[76:77], v[98:99], v[76:77]
	v_pk_mul_f32 v[80:81], v[92:93], v[80:81]
	v_pk_mul_f32 v[92:93], v[132:133], v[102:103]
	s_nop 0
	v_pk_mul_f32 v[80:81], v[92:93], v[80:81]
	s_nop 0
	v_cvt_pk_bf16_f32 v77, v77, v81
	v_cvt_pk_bf16_f32 v76, v76, v80
	v_or_b32_e32 v75, s88, v147
	v_mov_b64_e32 v[92:93], s[0:1]
	s_movk_i32 s4, 0x2800
	v_or_b32_e32 v96, 32, v1
	v_mad_i64_i32 v[80:81], s[0:1], v75, s4, v[92:93]
	v_mul_u32_u24_e32 v75, 0x410, v96
	v_lshlrev_b32_e32 v98, 16, v130
	v_add3_u32 v134, 0, v75, v74
	v_add_f32_e32 v74, v66, v84
	v_mul_f32_e32 v84, 0xbfb8aa3b, v98
	v_exp_f32_e32 v84, v84
	v_add_f32_e32 v75, v67, v85
	v_and_b32_e32 v102, 0xffff0000, v130
	v_lshl_add_u64 v[80:81], v[80:81], 0, v[90:91]
	v_add_f32_e32 v84, 1.0, v84
	v_mul_f32_e32 v75, 0xbfb8aa3b, v75
	v_rcp_f32_e32 v100, v84
	v_mul_f32_e32 v84, 0xbfb8aa3b, v102
	global_store_dwordx2 v[80:81], v[76:77], off offset:2560
	v_exp_f32_e32 v75, v75
	v_add_f32_e32 v77, v69, v87
	v_exp_f32_e32 v84, v84
	v_mul_f32_e32 v77, 0xbfb8aa3b, v77
	v_exp_f32_e32 v77, v77
	v_add_f32_e32 v75, 1.0, v75
	v_add_f32_e32 v84, 1.0, v84
	v_add_u32_e32 v95, 0x4000, v134
	v_rcp_f32_e32 v76, v75
	v_add_f32_e32 v75, v68, v86
	v_rcp_f32_e32 v130, v84
	ds_read2_b64 v[84:87], v95 offset0:32 offset1:36
	v_add_f32_e32 v77, 1.0, v77
	v_lshlrev_b32_e32 v99, 16, v131
	v_mul_f32_e32 v74, 0xbfb8aa3b, v74
	v_mul_f32_e32 v75, 0xbfb8aa3b, v75
	v_rcp_f32_e32 v77, v77
	v_mul_f32_e32 v101, 0xbfb8aa3b, v99
	v_exp_f32_e32 v74, v74
	v_exp_f32_e32 v75, v75
	v_exp_f32_e32 v101, v101
	v_and_b32_e32 v103, 0xffff0000, v131
	s_waitcnt lgkmcnt(0)
	v_lshlrev_b32_e32 v133, 16, v85
	v_lshlrev_b32_e32 v132, 16, v84
	v_and_b32_e32 v85, 0xffff0000, v85
	v_and_b32_e32 v84, 0xffff0000, v84
	v_add_f32_e32 v67, v67, v71
	v_pk_mul_f32 v[76:77], v[76:77], v[84:85]
	v_mul_f32_e32 v84, 0xbfb8aa3b, v103
	v_mul_f32_e32 v67, 0xbfb8aa3b, v67
	v_add_f32_e32 v74, 1.0, v74
	v_add_f32_e32 v75, 1.0, v75
	v_add_f32_e32 v101, 1.0, v101
	v_exp_f32_e32 v84, v84
	v_exp_f32_e32 v67, v67
	v_rcp_f32_e32 v74, v74
	v_rcp_f32_e32 v75, v75
	v_rcp_f32_e32 v101, v101
	v_add_f32_e32 v84, 1.0, v84
	v_add_f32_e32 v67, 1.0, v67
	v_pk_mul_f32 v[74:75], v[74:75], v[132:133]
	v_pk_mul_f32 v[98:99], v[100:101], v[98:99]
	v_rcp_f32_e32 v131, v84
	v_add_f32_e32 v66, v66, v70
	v_rcp_f32_e32 v70, v67
	v_add_f32_e32 v67, v68, v72
	v_add_f32_e32 v68, v69, v73
	v_pk_mul_f32 v[74:75], v[98:99], v[74:75]
	v_mul_f32_e32 v68, 0xbfb8aa3b, v68
	v_and_b32_e32 v98, 0xffff0000, v128
	v_exp_f32_e32 v68, v68
	v_mul_f32_e32 v73, 0xbfb8aa3b, v98
	v_exp_f32_e32 v73, v73
	v_pk_mul_f32 v[84:85], v[130:131], v[102:103]
	v_add_f32_e32 v68, 1.0, v68
	v_pk_mul_f32 v[76:77], v[84:85], v[76:77]
	s_nop 0
	v_cvt_pk_bf16_f32 v74, v74, v76
	v_cvt_pk_bf16_f32 v75, v75, v77
	v_rcp_f32_e32 v71, v68
	v_lshlrev_b32_e32 v69, 16, v129
	v_lshlrev_b32_e32 v68, 16, v128
	v_add_f32_e32 v73, 1.0, v73
	v_mul_f32_e32 v66, 0xbfb8aa3b, v66
	v_mul_f32_e32 v67, 0xbfb8aa3b, v67
	v_mul_f32_e32 v72, 0xbfb8aa3b, v68
	v_rcp_f32_e32 v100, v73
	v_mul_f32_e32 v73, 0xbfb8aa3b, v69
	v_or_b32_e32 v76, s88, v96
	v_exp_f32_e32 v66, v66
	v_exp_f32_e32 v67, v67
	v_exp_f32_e32 v72, v72
	v_exp_f32_e32 v73, v73
	v_mad_i64_i32 v[76:77], s[0:1], v76, s4, v[92:93]
	v_lshl_add_u64 v[84:85], v[76:77], 0, v[90:91]
	v_add_u32_e32 v96, 0x8000, v134
	global_store_dwordx2 v[84:85], v[74:75], off offset:2560
	ds_read2_b64 v[74:77], v96 offset0:64 offset1:68
	v_add_f32_e32 v66, 1.0, v66
	v_add_f32_e32 v67, 1.0, v67
	v_add_f32_e32 v72, 1.0, v72
	v_add_f32_e32 v73, 1.0, v73
	v_rcp_f32_e32 v66, v66
	v_rcp_f32_e32 v67, v67
	v_rcp_f32_e32 v72, v72
	v_rcp_f32_e32 v73, v73
	s_waitcnt lgkmcnt(0)
	v_lshlrev_b32_e32 v103, 16, v75
	v_lshlrev_b32_e32 v102, 16, v74
	v_pk_mul_f32 v[66:67], v[66:67], v[102:103]
	v_pk_mul_f32 v[68:69], v[72:73], v[68:69]
	v_and_b32_e32 v99, 0xffff0000, v129
	v_pk_mul_f32 v[66:67], v[68:69], v[66:67]
	v_and_b32_e32 v69, 0xffff0000, v75
	v_and_b32_e32 v68, 0xffff0000, v74
	v_pk_mul_f32 v[68:69], v[70:71], v[68:69]
	v_mul_f32_e32 v70, 0xbfb8aa3b, v99
	v_exp_f32_e32 v70, v70
	v_or3_b32 v1, v1, s88, 48
	v_and_b32_e32 v72, 0xffff0000, v126
	v_and_b32_e32 v73, 0xffff0000, v127
	v_add_f32_e32 v70, 1.0, v70
	v_rcp_f32_e32 v101, v70
	v_readlane_b32 s10, v255, 3
	v_readlane_b32 s11, v255, 4
	v_pk_mul_f32 v[70:71], v[100:101], v[98:99]
	s_nop 0
	v_pk_mul_f32 v[68:69], v[70:71], v[68:69]
	s_nop 0
	v_cvt_pk_bf16_f32 v69, v67, v69
	v_cvt_pk_bf16_f32 v68, v66, v68
	v_mad_i64_i32 v[66:67], s[0:1], v1, s4, v[92:93]
	v_add_f32_e32 v1, v46, v62
	v_mul_f32_e32 v1, 0xbfb8aa3b, v1
	v_exp_f32_e32 v1, v1
	v_lshl_add_u64 v[66:67], v[66:67], 0, v[90:91]
	global_store_dwordx2 v[66:67], v[68:69], off offset:2560
	v_lshlrev_b32_e32 v91, 16, v79
	v_add_f32_e32 v1, 1.0, v1
	v_rcp_f32_e32 v62, v1
	v_add_f32_e32 v1, v47, v63
	v_mul_f32_e32 v1, 0xbfb8aa3b, v1
	v_exp_f32_e32 v1, v1
	v_lshlrev_b32_e32 v90, 16, v78
	v_add_f32_e32 v1, 1.0, v1
	v_rcp_f32_e32 v68, v1
	v_add_f32_e32 v1, v48, v64
	v_mul_f32_e32 v1, 0xbfb8aa3b, v1
	v_exp_f32_e32 v1, v1
	v_lshlrev_b32_e32 v64, 16, v126
	v_add_f32_e32 v1, 1.0, v1
	v_rcp_f32_e32 v63, v1
	v_add_f32_e32 v1, v49, v65
	v_mul_f32_e32 v1, 0xbfb8aa3b, v1
	v_exp_f32_e32 v1, v1
	v_lshlrev_b32_e32 v65, 16, v127
	v_pk_mul_f32 v[62:63], v[62:63], v[90:91]
	v_add_f32_e32 v1, 1.0, v1
	v_rcp_f32_e32 v69, v1
	v_mul_f32_e32 v1, 0xbfb8aa3b, v64
	v_exp_f32_e32 v1, v1
	s_nop 0
	v_add_f32_e32 v1, 1.0, v1
	v_rcp_f32_e32 v70, v1
	v_mul_f32_e32 v1, 0xbfb8aa3b, v72
	v_exp_f32_e32 v1, v1
	s_nop 0
	v_add_f32_e32 v1, 1.0, v1
	v_rcp_f32_e32 v74, v1
	v_mul_f32_e32 v1, 0xbfb8aa3b, v65
	v_exp_f32_e32 v1, v1
	s_nop 0
	v_add_f32_e32 v1, 1.0, v1
	v_rcp_f32_e32 v71, v1
	v_mul_f32_e32 v1, 0xbfb8aa3b, v73
	v_exp_f32_e32 v1, v1
	v_pk_mul_f32 v[64:65], v[70:71], v[64:65]
	s_nop 0
	v_pk_mul_f32 v[62:63], v[64:65], v[62:63]
	v_add_f32_e32 v1, 1.0, v1
	v_rcp_f32_e32 v75, v1
	v_and_b32_e32 v65, 0xffff0000, v79
	v_and_b32_e32 v64, 0xffff0000, v78
	v_pk_mul_f32 v[64:65], v[68:69], v[64:65]
	v_pk_mul_f32 v[68:69], v[74:75], v[72:73]
	s_nop 0
	v_pk_mul_f32 v[64:65], v[68:69], v[64:65]
	s_nop 0
	v_cvt_pk_bf16_f32 v63, v63, v65
	v_add_f32_e32 v1, v46, v58
	v_mul_f32_e32 v1, 0xbfb8aa3b, v1
	v_exp_f32_e32 v1, v1
	v_cvt_pk_bf16_f32 v62, v62, v64
	v_add_f32_e32 v1, 1.0, v1
	v_rcp_f32_e32 v58, v1
	v_add_f32_e32 v1, v47, v59
	v_mul_f32_e32 v1, 0xbfb8aa3b, v1
	v_exp_f32_e32 v1, v1
	s_nop 0
	v_add_f32_e32 v1, 1.0, v1
	global_store_dwordx2 v[88:89], v[62:63], off offset:2592
	v_rcp_f32_e32 v62, v1
	v_add_f32_e32 v1, v48, v60
	v_mul_f32_e32 v1, 0xbfb8aa3b, v1
	v_exp_f32_e32 v1, v1
	v_lshlrev_b32_e32 v60, 16, v124
	v_and_b32_e32 v68, 0xffff0000, v124
	v_and_b32_e32 v69, 0xffff0000, v125
	v_add_f32_e32 v1, 1.0, v1
	v_rcp_f32_e32 v59, v1
	v_add_f32_e32 v1, v49, v61
	v_mul_f32_e32 v1, 0xbfb8aa3b, v1
	v_exp_f32_e32 v1, v1
	v_lshlrev_b32_e32 v61, 16, v125
	v_lshlrev_b32_e32 v73, 16, v83
	v_lshlrev_b32_e32 v72, 16, v82
	v_add_f32_e32 v1, 1.0, v1
	v_rcp_f32_e32 v63, v1
	v_mul_f32_e32 v1, 0xbfb8aa3b, v60
	v_exp_f32_e32 v1, v1
	v_pk_mul_f32 v[58:59], v[58:59], v[72:73]
	v_add_f32_e32 v1, 1.0, v1
	v_rcp_f32_e32 v64, v1
	v_mul_f32_e32 v1, 0xbfb8aa3b, v68
	v_exp_f32_e32 v1, v1
	s_nop 0
	v_add_f32_e32 v1, 1.0, v1
	v_rcp_f32_e32 v70, v1
	v_mul_f32_e32 v1, 0xbfb8aa3b, v61
	v_exp_f32_e32 v1, v1
	s_nop 0
	v_add_f32_e32 v1, 1.0, v1
	v_rcp_f32_e32 v65, v1
	v_mul_f32_e32 v1, 0xbfb8aa3b, v69
	v_exp_f32_e32 v1, v1
	v_pk_mul_f32 v[60:61], v[64:65], v[60:61]
	s_nop 0
	v_pk_mul_f32 v[58:59], v[60:61], v[58:59]
	v_add_f32_e32 v1, 1.0, v1
	v_rcp_f32_e32 v71, v1
	v_and_b32_e32 v61, 0xffff0000, v83
	v_and_b32_e32 v60, 0xffff0000, v82
	v_pk_mul_f32 v[60:61], v[62:63], v[60:61]
	v_pk_mul_f32 v[62:63], v[70:71], v[68:69]
	s_nop 0
	v_pk_mul_f32 v[60:61], v[62:63], v[60:61]
	s_nop 0
	v_cvt_pk_bf16_f32 v59, v59, v61
	v_add_f32_e32 v1, v46, v54
	v_mul_f32_e32 v1, 0xbfb8aa3b, v1
	v_exp_f32_e32 v1, v1
	v_cvt_pk_bf16_f32 v58, v58, v60
	v_add_f32_e32 v1, 1.0, v1
	v_rcp_f32_e32 v54, v1
	v_add_f32_e32 v1, v47, v55
	v_mul_f32_e32 v1, 0xbfb8aa3b, v1
	v_exp_f32_e32 v1, v1
	s_nop 0
	v_add_f32_e32 v1, 1.0, v1
	global_store_dwordx2 v[80:81], v[58:59], off offset:2592
	v_rcp_f32_e32 v58, v1
	v_add_f32_e32 v1, v48, v56
	v_mul_f32_e32 v1, 0xbfb8aa3b, v1
	v_exp_f32_e32 v1, v1
	v_lshlrev_b32_e32 v56, 16, v122
	v_and_b32_e32 v62, 0xffff0000, v122
	v_and_b32_e32 v63, 0xffff0000, v123
	v_add_f32_e32 v1, 1.0, v1
	v_rcp_f32_e32 v55, v1
	v_add_f32_e32 v1, v49, v57
	v_mul_f32_e32 v1, 0xbfb8aa3b, v1
	v_exp_f32_e32 v1, v1
	v_lshlrev_b32_e32 v57, 16, v123
	v_lshlrev_b32_e32 v69, 16, v87
	v_lshlrev_b32_e32 v68, 16, v86
	v_add_f32_e32 v1, 1.0, v1
	v_rcp_f32_e32 v59, v1
	v_mul_f32_e32 v1, 0xbfb8aa3b, v56
	v_exp_f32_e32 v1, v1
	v_pk_mul_f32 v[54:55], v[54:55], v[68:69]
	v_add_f32_e32 v1, 1.0, v1
	v_rcp_f32_e32 v60, v1
	v_mul_f32_e32 v1, 0xbfb8aa3b, v62
	v_exp_f32_e32 v1, v1
	s_nop 0
	v_add_f32_e32 v1, 1.0, v1
	v_rcp_f32_e32 v64, v1
	v_mul_f32_e32 v1, 0xbfb8aa3b, v57
	v_exp_f32_e32 v1, v1
	s_nop 0
	v_add_f32_e32 v1, 1.0, v1
	v_rcp_f32_e32 v61, v1
	v_mul_f32_e32 v1, 0xbfb8aa3b, v63
	v_exp_f32_e32 v1, v1
	v_pk_mul_f32 v[56:57], v[60:61], v[56:57]
	s_nop 0
	v_pk_mul_f32 v[54:55], v[56:57], v[54:55]
	v_add_f32_e32 v1, 1.0, v1
	v_rcp_f32_e32 v65, v1
	v_and_b32_e32 v57, 0xffff0000, v87
	v_and_b32_e32 v56, 0xffff0000, v86
	v_pk_mul_f32 v[56:57], v[58:59], v[56:57]
	v_pk_mul_f32 v[58:59], v[64:65], v[62:63]
	s_nop 0
	v_pk_mul_f32 v[56:57], v[58:59], v[56:57]
	s_nop 0
	v_cvt_pk_bf16_f32 v55, v55, v57
	v_add_f32_e32 v1, v46, v50
	v_mul_f32_e32 v1, 0xbfb8aa3b, v1
	v_exp_f32_e32 v1, v1
	v_cvt_pk_bf16_f32 v54, v54, v56
	v_add_f32_e32 v1, 1.0, v1
	v_rcp_f32_e32 v46, v1
	v_add_f32_e32 v1, v47, v51
	v_mul_f32_e32 v1, 0xbfb8aa3b, v1
	v_exp_f32_e32 v1, v1
	s_nop 0
	v_add_f32_e32 v1, 1.0, v1
	v_rcp_f32_e32 v50, v1
	v_add_f32_e32 v1, v48, v52
	v_mul_f32_e32 v1, 0xbfb8aa3b, v1
	v_exp_f32_e32 v1, v1
	v_lshlrev_b32_e32 v48, 16, v120
	global_store_dwordx2 v[84:85], v[54:55], off offset:2592
	v_and_b32_e32 v54, 0xffff0000, v120
	v_add_f32_e32 v1, 1.0, v1
	v_rcp_f32_e32 v47, v1
	v_add_f32_e32 v1, v49, v53
	v_mul_f32_e32 v1, 0xbfb8aa3b, v1
	v_exp_f32_e32 v1, v1
	v_lshlrev_b32_e32 v49, 16, v121
	v_and_b32_e32 v55, 0xffff0000, v121
	v_lshlrev_b32_e32 v59, 16, v77
	v_add_f32_e32 v1, 1.0, v1
	v_rcp_f32_e32 v51, v1
	v_mul_f32_e32 v1, 0xbfb8aa3b, v48
	v_exp_f32_e32 v1, v1
	v_lshlrev_b32_e32 v58, 16, v76
	v_pk_mul_f32 v[46:47], v[46:47], v[58:59]
	v_add_f32_e32 v1, 1.0, v1
	v_rcp_f32_e32 v52, v1
	v_mul_f32_e32 v1, 0xbfb8aa3b, v54
	v_exp_f32_e32 v1, v1
	s_nop 0
	v_add_f32_e32 v1, 1.0, v1
	v_rcp_f32_e32 v56, v1
	v_mul_f32_e32 v1, 0xbfb8aa3b, v49
	v_exp_f32_e32 v1, v1
	s_nop 0
	v_add_f32_e32 v1, 1.0, v1
	v_rcp_f32_e32 v53, v1
	v_mul_f32_e32 v1, 0xbfb8aa3b, v55
	v_exp_f32_e32 v1, v1
	v_pk_mul_f32 v[48:49], v[52:53], v[48:49]
	s_nop 0
	v_pk_mul_f32 v[46:47], v[48:49], v[46:47]
	v_add_f32_e32 v1, 1.0, v1
	v_rcp_f32_e32 v57, v1
	v_and_b32_e32 v49, 0xffff0000, v77
	v_and_b32_e32 v48, 0xffff0000, v76
	v_pk_mul_f32 v[48:49], v[50:51], v[48:49]
	v_pk_mul_f32 v[50:51], v[56:57], v[54:55]
	s_nop 0
	v_pk_mul_f32 v[48:49], v[50:51], v[48:49]
	s_nop 0
	v_cvt_pk_bf16_f32 v47, v47, v49
	v_add_f32_e32 v1, v26, v42
	v_mul_f32_e32 v1, 0xbfb8aa3b, v1
	v_exp_f32_e32 v1, v1
	v_cvt_pk_bf16_f32 v46, v46, v48
	v_add_f32_e32 v1, 1.0, v1
	v_rcp_f32_e32 v42, v1
	v_add_f32_e32 v1, v27, v43
	v_mul_f32_e32 v1, 0xbfb8aa3b, v1
	v_exp_f32_e32 v1, v1
	v_and_b32_e32 v54, 0xffff0000, v118
	v_and_b32_e32 v55, 0xffff0000, v119
	v_add_f32_e32 v1, 1.0, v1
	v_rcp_f32_e32 v50, v1
	v_add_f32_e32 v1, v28, v44
	v_mul_f32_e32 v1, 0xbfb8aa3b, v1
	v_exp_f32_e32 v1, v1
	v_lshlrev_b32_e32 v44, 16, v118
	v_add_f32_e32 v1, 1.0, v1
	v_rcp_f32_e32 v43, v1
	v_add_f32_e32 v1, v29, v45
	v_mul_f32_e32 v1, 0xbfb8aa3b, v1
	v_exp_f32_e32 v1, v1
	v_lshlrev_b32_e32 v45, 16, v119
	global_store_dwordx2 v[66:67], v[46:47], off offset:2592
	ds_read2_b64 v[46:49], v97 offset0:40 offset1:44
	v_add_f32_e32 v1, 1.0, v1
	v_rcp_f32_e32 v51, v1
	v_mul_f32_e32 v1, 0xbfb8aa3b, v44
	v_exp_f32_e32 v1, v1
	s_waitcnt lgkmcnt(0)
	v_lshlrev_b32_e32 v59, 16, v47
	v_lshlrev_b32_e32 v58, 16, v46
	v_pk_mul_f32 v[42:43], v[42:43], v[58:59]
	v_add_f32_e32 v1, 1.0, v1
	v_rcp_f32_e32 v52, v1
	v_mul_f32_e32 v1, 0xbfb8aa3b, v54
	v_exp_f32_e32 v1, v1
	s_nop 0
	v_add_f32_e32 v1, 1.0, v1
	v_rcp_f32_e32 v56, v1
	v_mul_f32_e32 v1, 0xbfb8aa3b, v45
	v_exp_f32_e32 v1, v1
	s_nop 0
	v_add_f32_e32 v1, 1.0, v1
	v_rcp_f32_e32 v53, v1
	v_mul_f32_e32 v1, 0xbfb8aa3b, v55
	v_exp_f32_e32 v1, v1
	v_pk_mul_f32 v[44:45], v[52:53], v[44:45]
	s_nop 0
	v_pk_mul_f32 v[42:43], v[44:45], v[42:43]
	v_add_f32_e32 v1, 1.0, v1
	v_rcp_f32_e32 v57, v1
	v_and_b32_e32 v45, 0xffff0000, v47
	v_and_b32_e32 v44, 0xffff0000, v46
	v_pk_mul_f32 v[44:45], v[50:51], v[44:45]
	v_pk_mul_f32 v[46:47], v[56:57], v[54:55]
	s_nop 0
	v_pk_mul_f32 v[44:45], v[46:47], v[44:45]
	s_nop 0
	v_cvt_pk_bf16_f32 v43, v43, v45
	v_add_f32_e32 v1, v26, v38
	v_mul_f32_e32 v1, 0xbfb8aa3b, v1
	v_exp_f32_e32 v1, v1
	v_cvt_pk_bf16_f32 v42, v42, v44
	v_add_f32_e32 v1, 1.0, v1
	global_store_dwordx2 v[88:89], v[42:43], off offset:2624
	v_rcp_f32_e32 v42, v1
	v_add_f32_e32 v1, v27, v39
	v_mul_f32_e32 v1, 0xbfb8aa3b, v1
	v_exp_f32_e32 v1, v1
	v_lshlrev_b32_e32 v46, 16, v116
	v_and_b32_e32 v52, 0xffff0000, v116
	v_lshlrev_b32_e32 v47, 16, v117
	v_add_f32_e32 v1, 1.0, v1
	v_rcp_f32_e32 v44, v1
	v_add_f32_e32 v1, v28, v40
	v_mul_f32_e32 v1, 0xbfb8aa3b, v1
	v_exp_f32_e32 v1, v1
	v_and_b32_e32 v53, 0xffff0000, v117
	v_add_f32_e32 v1, 1.0, v1
	v_rcp_f32_e32 v43, v1
	v_add_f32_e32 v1, v29, v41
	v_mul_f32_e32 v1, 0xbfb8aa3b, v1
	v_exp_f32_e32 v1, v1
	ds_read2_b64 v[38:41], v94 offset0:40 offset1:44
	v_add_f32_e32 v1, 1.0, v1
	v_rcp_f32_e32 v45, v1
	v_mul_f32_e32 v1, 0xbfb8aa3b, v46
	v_exp_f32_e32 v1, v1
	s_waitcnt lgkmcnt(0)
	v_lshlrev_b32_e32 v57, 16, v39
	v_lshlrev_b32_e32 v56, 16, v38
	v_pk_mul_f32 v[42:43], v[42:43], v[56:57]
	v_add_f32_e32 v1, 1.0, v1
	v_rcp_f32_e32 v50, v1
	v_mul_f32_e32 v1, 0xbfb8aa3b, v52
	v_exp_f32_e32 v1, v1
	v_and_b32_e32 v39, 0xffff0000, v39
	v_and_b32_e32 v38, 0xffff0000, v38
	v_pk_mul_f32 v[38:39], v[44:45], v[38:39]
	v_add_f32_e32 v1, 1.0, v1
	v_rcp_f32_e32 v54, v1
	v_mul_f32_e32 v1, 0xbfb8aa3b, v47
	v_exp_f32_e32 v1, v1
	s_nop 0
	v_add_f32_e32 v1, 1.0, v1
	v_rcp_f32_e32 v51, v1
	v_mul_f32_e32 v1, 0xbfb8aa3b, v53
	v_exp_f32_e32 v1, v1
	v_pk_mul_f32 v[46:47], v[50:51], v[46:47]
	s_nop 0
	v_pk_mul_f32 v[42:43], v[46:47], v[42:43]
	v_add_f32_e32 v1, 1.0, v1
	v_rcp_f32_e32 v55, v1
	v_and_b32_e32 v50, 0xffff0000, v114
	v_pk_mul_f32 v[44:45], v[54:55], v[52:53]
	v_and_b32_e32 v51, 0xffff0000, v115
	v_pk_mul_f32 v[38:39], v[44:45], v[38:39]
	s_nop 0
	v_cvt_pk_bf16_f32 v39, v43, v39
	v_add_f32_e32 v1, v26, v34
	v_mul_f32_e32 v1, 0xbfb8aa3b, v1
	v_exp_f32_e32 v1, v1
	v_cvt_pk_bf16_f32 v42, v42, v42
	v_cvt_pk_bf16_f32 v38, v38, v38
	v_add_f32_e32 v1, 1.0, v1
	v_rcp_f32_e32 v34, v1
	v_add_f32_e32 v1, v27, v35
	v_mul_f32_e32 v1, 0xbfb8aa3b, v1
	v_exp_f32_e32 v1, v1
	v_bfi_b32 v38, s33, v38, v42
	v_lshlrev_b32_e32 v44, 16, v114
	v_add_f32_e32 v1, 1.0, v1
	v_rcp_f32_e32 v42, v1
	v_add_f32_e32 v1, v28, v36
	v_mul_f32_e32 v1, 0xbfb8aa3b, v1
	v_exp_f32_e32 v1, v1
	v_lshlrev_b32_e32 v45, 16, v115
	global_store_dwordx2 v[80:81], v[38:39], off offset:2624
	v_add_f32_e32 v1, 1.0, v1
	v_rcp_f32_e32 v35, v1
	v_add_f32_e32 v1, v29, v37
	v_mul_f32_e32 v1, 0xbfb8aa3b, v1
	v_exp_f32_e32 v1, v1
	ds_read2_b64 v[36:39], v95 offset0:40 offset1:44
	v_add_f32_e32 v1, 1.0, v1
	v_rcp_f32_e32 v43, v1
	v_mul_f32_e32 v1, 0xbfb8aa3b, v44
	v_exp_f32_e32 v1, v1
	s_waitcnt lgkmcnt(0)
	v_lshlrev_b32_e32 v55, 16, v37
	v_lshlrev_b32_e32 v54, 16, v36
	v_pk_mul_f32 v[34:35], v[34:35], v[54:55]
	v_add_f32_e32 v1, 1.0, v1
	v_rcp_f32_e32 v46, v1
	v_mul_f32_e32 v1, 0xbfb8aa3b, v50
	v_exp_f32_e32 v1, v1
	v_and_b32_e32 v37, 0xffff0000, v37
	v_and_b32_e32 v36, 0xffff0000, v36
	v_pk_mul_f32 v[36:37], v[42:43], v[36:37]
	v_add_f32_e32 v1, 1.0, v1
	v_rcp_f32_e32 v52, v1
	v_mul_f32_e32 v1, 0xbfb8aa3b, v45
	v_exp_f32_e32 v1, v1
	s_nop 0
	v_add_f32_e32 v1, 1.0, v1
	v_rcp_f32_e32 v47, v1
	v_mul_f32_e32 v1, 0xbfb8aa3b, v51
	v_exp_f32_e32 v1, v1
	v_pk_mul_f32 v[44:45], v[46:47], v[44:45]
	s_nop 0
	v_pk_mul_f32 v[34:35], v[44:45], v[34:35]
	v_add_f32_e32 v1, 1.0, v1
	v_rcp_f32_e32 v53, v1
	s_nop 0
	v_pk_mul_f32 v[42:43], v[52:53], v[50:51]
	s_nop 0
	v_pk_mul_f32 v[36:37], v[42:43], v[36:37]
	s_nop 0
	v_cvt_pk_bf16_f32 v35, v35, v37
	v_add_f32_e32 v1, v26, v30
	v_mul_f32_e32 v1, 0xbfb8aa3b, v1
	v_exp_f32_e32 v1, v1
	v_cvt_pk_bf16_f32 v34, v34, v34
	v_cvt_pk_bf16_f32 v36, v36, v36
	v_add_f32_e32 v1, 1.0, v1
	v_rcp_f32_e32 v26, v1
	v_add_f32_e32 v1, v27, v31
	v_mul_f32_e32 v1, 0xbfb8aa3b, v1
	v_exp_f32_e32 v1, v1
	v_and_b32_e32 v42, 0xffff0000, v112
	v_and_b32_e32 v43, 0xffff0000, v113
	v_add_f32_e32 v1, 1.0, v1
	v_rcp_f32_e32 v30, v1
	v_add_f32_e32 v1, v28, v32
	v_mul_f32_e32 v1, 0xbfb8aa3b, v1
	v_exp_f32_e32 v1, v1
	v_lshlrev_b32_e32 v28, 16, v112
	v_bfi_b32 v34, s33, v36, v34
	global_store_dwordx2 v[84:85], v[34:35], off offset:2624
	v_add_f32_e32 v1, 1.0, v1
	v_rcp_f32_e32 v27, v1
	v_add_f32_e32 v1, v29, v33
	v_mul_f32_e32 v1, 0xbfb8aa3b, v1
	v_exp_f32_e32 v1, v1
	v_lshlrev_b32_e32 v29, 16, v113
	ds_read2_b64 v[34:37], v96 offset0:72 offset1:76
	v_add_f32_e32 v1, 1.0, v1
	v_rcp_f32_e32 v31, v1
	v_mul_f32_e32 v1, 0xbfb8aa3b, v28
	v_exp_f32_e32 v1, v1
	s_waitcnt lgkmcnt(0)
	v_lshlrev_b32_e32 v47, 16, v35
	v_lshlrev_b32_e32 v46, 16, v34
	v_pk_mul_f32 v[26:27], v[26:27], v[46:47]
	v_add_f32_e32 v1, 1.0, v1
	v_rcp_f32_e32 v32, v1
	v_mul_f32_e32 v1, 0xbfb8aa3b, v42
	v_exp_f32_e32 v1, v1
	s_nop 0
	v_add_f32_e32 v1, 1.0, v1
	v_rcp_f32_e32 v44, v1
	v_mul_f32_e32 v1, 0xbfb8aa3b, v29
	v_exp_f32_e32 v1, v1
	s_nop 0
	v_add_f32_e32 v1, 1.0, v1
	v_rcp_f32_e32 v33, v1
	v_mul_f32_e32 v1, 0xbfb8aa3b, v43
	v_exp_f32_e32 v1, v1
	v_pk_mul_f32 v[28:29], v[32:33], v[28:29]
	s_nop 0
	v_pk_mul_f32 v[26:27], v[28:29], v[26:27]
	v_add_f32_e32 v1, 1.0, v1
	v_rcp_f32_e32 v45, v1
	v_and_b32_e32 v29, 0xffff0000, v35
	v_and_b32_e32 v28, 0xffff0000, v34
	v_pk_mul_f32 v[28:29], v[30:31], v[28:29]
	v_pk_mul_f32 v[30:31], v[44:45], v[42:43]
	s_nop 0
	v_pk_mul_f32 v[28:29], v[30:31], v[28:29]
	s_nop 0
	v_cvt_pk_bf16_f32 v27, v27, v29
	v_add_f32_e32 v1, v6, v22
	v_mul_f32_e32 v1, 0xbfb8aa3b, v1
	v_exp_f32_e32 v1, v1
	v_cvt_pk_bf16_f32 v26, v26, v28
	v_add_f32_e32 v1, 1.0, v1
	v_rcp_f32_e32 v22, v1
	v_add_f32_e32 v1, v7, v23
	v_mul_f32_e32 v1, 0xbfb8aa3b, v1
	v_exp_f32_e32 v1, v1
	s_nop 0
	v_add_f32_e32 v1, 1.0, v1
	global_store_dwordx2 v[66:67], v[26:27], off offset:2624
	v_rcp_f32_e32 v26, v1
	v_add_f32_e32 v1, v8, v24
	v_mul_f32_e32 v1, 0xbfb8aa3b, v1
	v_exp_f32_e32 v1, v1
	v_lshlrev_b32_e32 v24, 16, v110
	v_and_b32_e32 v30, 0xffff0000, v110
	v_and_b32_e32 v31, 0xffff0000, v111
	v_add_f32_e32 v1, 1.0, v1
	v_rcp_f32_e32 v23, v1
	v_add_f32_e32 v1, v9, v25
	v_mul_f32_e32 v1, 0xbfb8aa3b, v1
	v_exp_f32_e32 v1, v1
	v_lshlrev_b32_e32 v25, 16, v111
	v_lshlrev_b32_e32 v35, 16, v49
	v_lshlrev_b32_e32 v34, 16, v48
	v_add_f32_e32 v1, 1.0, v1
	v_rcp_f32_e32 v27, v1
	v_mul_f32_e32 v1, 0xbfb8aa3b, v24
	v_exp_f32_e32 v1, v1
	v_pk_mul_f32 v[22:23], v[22:23], v[34:35]
	v_add_f32_e32 v1, 1.0, v1
	v_rcp_f32_e32 v28, v1
	v_mul_f32_e32 v1, 0xbfb8aa3b, v30
	v_exp_f32_e32 v1, v1
	s_nop 0
	v_add_f32_e32 v1, 1.0, v1
	v_rcp_f32_e32 v32, v1
	v_mul_f32_e32 v1, 0xbfb8aa3b, v25
	v_exp_f32_e32 v1, v1
	s_nop 0
	v_add_f32_e32 v1, 1.0, v1
	v_rcp_f32_e32 v29, v1
	v_mul_f32_e32 v1, 0xbfb8aa3b, v31
	v_exp_f32_e32 v1, v1
	v_pk_mul_f32 v[24:25], v[28:29], v[24:25]
	s_nop 0
	v_pk_mul_f32 v[22:23], v[24:25], v[22:23]
	v_add_f32_e32 v1, 1.0, v1
	v_rcp_f32_e32 v33, v1
	v_and_b32_e32 v25, 0xffff0000, v49
	v_and_b32_e32 v24, 0xffff0000, v48
	v_pk_mul_f32 v[24:25], v[26:27], v[24:25]
	v_pk_mul_f32 v[26:27], v[32:33], v[30:31]
	s_nop 0
	v_pk_mul_f32 v[24:25], v[26:27], v[24:25]
	s_nop 0
	v_cvt_pk_bf16_f32 v23, v23, v25
	v_add_f32_e32 v1, v6, v18
	v_mul_f32_e32 v1, 0xbfb8aa3b, v1
	v_exp_f32_e32 v1, v1
	v_cvt_pk_bf16_f32 v22, v22, v24
	v_add_f32_e32 v1, 1.0, v1
	v_rcp_f32_e32 v18, v1
	v_add_f32_e32 v1, v7, v19
	v_mul_f32_e32 v1, 0xbfb8aa3b, v1
	v_exp_f32_e32 v1, v1
	s_nop 0
	v_add_f32_e32 v1, 1.0, v1
	global_store_dwordx2 v[88:89], v[22:23], off offset:2656
	v_rcp_f32_e32 v22, v1
	v_add_f32_e32 v1, v8, v20
	v_mul_f32_e32 v1, 0xbfb8aa3b, v1
	v_exp_f32_e32 v1, v1
	v_lshlrev_b32_e32 v20, 16, v108
	v_and_b32_e32 v26, 0xffff0000, v108
	v_and_b32_e32 v27, 0xffff0000, v109
	v_add_f32_e32 v1, 1.0, v1
	v_rcp_f32_e32 v19, v1
	v_add_f32_e32 v1, v9, v21
	v_mul_f32_e32 v1, 0xbfb8aa3b, v1
	v_exp_f32_e32 v1, v1
	v_lshlrev_b32_e32 v21, 16, v109
	v_lshlrev_b32_e32 v31, 16, v41
	v_lshlrev_b32_e32 v30, 16, v40
	v_add_f32_e32 v1, 1.0, v1
	v_rcp_f32_e32 v23, v1
	v_mul_f32_e32 v1, 0xbfb8aa3b, v20
	v_exp_f32_e32 v1, v1
	v_pk_mul_f32 v[18:19], v[18:19], v[30:31]
	v_add_f32_e32 v1, 1.0, v1
	v_rcp_f32_e32 v24, v1
	v_mul_f32_e32 v1, 0xbfb8aa3b, v26
	v_exp_f32_e32 v1, v1
	s_nop 0
	v_add_f32_e32 v1, 1.0, v1
	v_rcp_f32_e32 v28, v1
	v_mul_f32_e32 v1, 0xbfb8aa3b, v21
	v_exp_f32_e32 v1, v1
	s_nop 0
	v_add_f32_e32 v1, 1.0, v1
	v_rcp_f32_e32 v25, v1
	v_mul_f32_e32 v1, 0xbfb8aa3b, v27
	v_exp_f32_e32 v1, v1
	v_pk_mul_f32 v[20:21], v[24:25], v[20:21]
	s_nop 0
	v_pk_mul_f32 v[18:19], v[20:21], v[18:19]
	v_add_f32_e32 v1, 1.0, v1
	v_rcp_f32_e32 v29, v1
	v_and_b32_e32 v21, 0xffff0000, v41
	v_and_b32_e32 v20, 0xffff0000, v40
	v_pk_mul_f32 v[20:21], v[22:23], v[20:21]
	v_pk_mul_f32 v[22:23], v[28:29], v[26:27]
	s_nop 0
	v_pk_mul_f32 v[20:21], v[22:23], v[20:21]
	s_nop 0
	v_cvt_pk_bf16_f32 v19, v19, v21
	v_add_f32_e32 v1, v6, v14
	v_mul_f32_e32 v1, 0xbfb8aa3b, v1
	v_exp_f32_e32 v1, v1
	v_cvt_pk_bf16_f32 v18, v18, v20
	v_add_f32_e32 v1, 1.0, v1
	v_rcp_f32_e32 v14, v1
	v_add_f32_e32 v1, v7, v15
	v_mul_f32_e32 v1, 0xbfb8aa3b, v1
	v_exp_f32_e32 v1, v1
	s_nop 0
	v_add_f32_e32 v1, 1.0, v1
	global_store_dwordx2 v[80:81], v[18:19], off offset:2656
	v_rcp_f32_e32 v18, v1
	v_add_f32_e32 v1, v8, v16
	v_mul_f32_e32 v1, 0xbfb8aa3b, v1
	v_exp_f32_e32 v1, v1
	v_lshlrev_b32_e32 v16, 16, v106
	v_and_b32_e32 v22, 0xffff0000, v106
	v_and_b32_e32 v23, 0xffff0000, v107
	v_add_f32_e32 v1, 1.0, v1
	v_rcp_f32_e32 v15, v1
	v_add_f32_e32 v1, v9, v17
	v_mul_f32_e32 v1, 0xbfb8aa3b, v1
	v_exp_f32_e32 v1, v1
	v_lshlrev_b32_e32 v17, 16, v107
	v_lshlrev_b32_e32 v27, 16, v39
	v_lshlrev_b32_e32 v26, 16, v38
	v_add_f32_e32 v1, 1.0, v1
	v_rcp_f32_e32 v19, v1
	v_mul_f32_e32 v1, 0xbfb8aa3b, v16
	v_exp_f32_e32 v1, v1
	v_pk_mul_f32 v[14:15], v[14:15], v[26:27]
	v_add_f32_e32 v1, 1.0, v1
	v_rcp_f32_e32 v20, v1
	v_mul_f32_e32 v1, 0xbfb8aa3b, v22
	v_exp_f32_e32 v1, v1
	s_nop 0
	v_add_f32_e32 v1, 1.0, v1
	v_rcp_f32_e32 v24, v1
	v_mul_f32_e32 v1, 0xbfb8aa3b, v17
	v_exp_f32_e32 v1, v1
	s_nop 0
	v_add_f32_e32 v1, 1.0, v1
	v_rcp_f32_e32 v21, v1
	v_mul_f32_e32 v1, 0xbfb8aa3b, v23
	v_exp_f32_e32 v1, v1
	v_pk_mul_f32 v[16:17], v[20:21], v[16:17]
	s_nop 0
	v_pk_mul_f32 v[14:15], v[16:17], v[14:15]
	v_add_f32_e32 v1, 1.0, v1
	v_rcp_f32_e32 v25, v1
	v_and_b32_e32 v17, 0xffff0000, v39
	v_and_b32_e32 v16, 0xffff0000, v38
	v_pk_mul_f32 v[16:17], v[18:19], v[16:17]
	v_pk_mul_f32 v[18:19], v[24:25], v[22:23]
	s_nop 0
	v_pk_mul_f32 v[16:17], v[18:19], v[16:17]
	s_nop 0
	v_cvt_pk_bf16_f32 v15, v15, v17
	v_add_f32_e32 v1, v6, v10
	v_mul_f32_e32 v1, 0xbfb8aa3b, v1
	v_exp_f32_e32 v1, v1
	v_cvt_pk_bf16_f32 v14, v14, v16
	v_add_f32_e32 v1, 1.0, v1
	v_rcp_f32_e32 v6, v1
	v_add_f32_e32 v1, v7, v11
	v_mul_f32_e32 v1, 0xbfb8aa3b, v1
	v_exp_f32_e32 v1, v1
	s_nop 0
	v_add_f32_e32 v1, 1.0, v1
	v_rcp_f32_e32 v10, v1
	v_add_f32_e32 v1, v8, v12
	v_mul_f32_e32 v1, 0xbfb8aa3b, v1
	v_exp_f32_e32 v1, v1
	v_lshlrev_b32_e32 v8, 16, v104
	global_store_dwordx2 v[84:85], v[14:15], off offset:2656
	v_and_b32_e32 v14, 0xffff0000, v104
	v_add_f32_e32 v1, 1.0, v1
	v_rcp_f32_e32 v7, v1
	v_add_f32_e32 v1, v9, v13
	v_mul_f32_e32 v1, 0xbfb8aa3b, v1
	v_exp_f32_e32 v1, v1
	v_lshlrev_b32_e32 v9, 16, v105
	v_and_b32_e32 v15, 0xffff0000, v105
	v_lshlrev_b32_e32 v19, 16, v37
	v_add_f32_e32 v1, 1.0, v1
	v_rcp_f32_e32 v11, v1
	v_mul_f32_e32 v1, 0xbfb8aa3b, v8
	v_exp_f32_e32 v1, v1
	v_lshlrev_b32_e32 v18, 16, v36
	v_pk_mul_f32 v[6:7], v[6:7], v[18:19]
	v_add_f32_e32 v1, 1.0, v1
	v_rcp_f32_e32 v12, v1
	v_mul_f32_e32 v1, 0xbfb8aa3b, v14
	v_exp_f32_e32 v1, v1
	s_nop 0
	v_add_f32_e32 v1, 1.0, v1
	v_rcp_f32_e32 v16, v1
	v_mul_f32_e32 v1, 0xbfb8aa3b, v9
	v_exp_f32_e32 v1, v1
	s_nop 0
	v_add_f32_e32 v1, 1.0, v1
	v_rcp_f32_e32 v13, v1
	v_mul_f32_e32 v1, 0xbfb8aa3b, v15
	v_exp_f32_e32 v1, v1
	v_pk_mul_f32 v[8:9], v[12:13], v[8:9]
	s_nop 0
	v_pk_mul_f32 v[6:7], v[8:9], v[6:7]
	v_add_f32_e32 v1, 1.0, v1
	v_rcp_f32_e32 v17, v1
	v_and_b32_e32 v9, 0xffff0000, v37
	v_and_b32_e32 v8, 0xffff0000, v36
	v_pk_mul_f32 v[8:9], v[10:11], v[8:9]
	v_pk_mul_f32 v[10:11], v[16:17], v[14:15]
	s_nop 0
	v_pk_mul_f32 v[8:9], v[10:11], v[8:9]
	s_nop 0
	v_cvt_pk_bf16_f32 v7, v7, v9
	v_cvt_pk_bf16_f32 v6, v6, v8
	global_store_dwordx2 v[66:67], v[6:7], off offset:2656
	s_barrier
